# GQA tile loop rewritten by hand (rotated single-tile loop, fragment ring, mid-body barrier); softmax row sums via one 16x16x32 MFMA per 16-key block instead of 32x32x16 in GQA and diff far tiles; mLST
# speedup vs baseline: 1.0386x; 1.0277x over previous
.LBB0_1019:
	s_waitcnt vmcnt(1)
	s_nop 7
	v_mbcnt_lo_u32_b32 v80, -1, 0
	v_mbcnt_hi_u32_b32 v80, -1, v80
	v_and_b32_e32 v81, 15, v80
	v_lshlrev_b32_e32 v81, 2, v81
	v_and_b32_e32 v80, 16, v80
	v_cmp_ne_u32_e32 vcc, 0, v80
	ds_bpermute_b32 v82, v81, v248
	ds_bpermute_b32 v81, v81, v249
	s_waitcnt lgkmcnt(0)
	v_cndmask_b32_e32 v80, v82, v81, vcc
	v_add_f32_e32 v80, v64, v80
	v_mul_f32_e32 v133, 0.5, v80

.LBB0_1033:
.LBB0_1034:
	s_or_saveexec_b64 s[4:5], s[12:13]
	v_sub_f32_e32 v204, v201, v143
	v_sub_f32_e32 v205, v202, v143
	s_xor_b64 exec, exec, s[4:5]
	s_cbranch_execz .LBB0_1044
	v_mbcnt_lo_u32_b32 v36, -1, 0
	v_mbcnt_hi_u32_b32 v36, -1, v36
	s_nop 5
	global_load_dwordx4 v[0:3], v[144:145], off
	global_load_dwordx4 v[4:7], v[144:145], off offset:16
	global_load_dwordx4 v[8:11], v[144:145], off offset:64
	global_load_dwordx4 v[12:15], v[144:145], off offset:80
	global_load_dwordx4 v[16:19], v[144:145], off offset:128
	global_load_dwordx4 v[20:23], v[144:145], off offset:144
	global_load_dwordx4 v[24:27], v[144:145], off offset:192
	global_load_dwordx4 v[28:31], v[144:145], off offset:208
	global_load_dwordx4 v[32:35], v[170:171], off offset:128
	v_mov_b32_e32 v175, v177
	v_lshlrev_b32_e32 v38, 2, v36
	v_lshl_add_u64 v[36:37], s[10:11], 0, v[174:175]
	v_xor_b32_e32 v38, 0x80, v38
	v_lshl_add_u64 v[44:45], v[36:37], 0, v[152:153]
	s_waitcnt vmcnt(11)
	ds_bpermute_b32 v48, v38, v96
	v_lshl_add_u64 v[46:47], v[36:37], 0, v[154:155]
	global_load_dwordx4 v[36:39], v[44:45], off
	global_load_dwordx4 v[40:43], v[46:47], off
	s_mov_b32 s0, 0x3e38aa3b
	s_waitcnt lgkmcnt(0)
	v_add_f32_e32 v48, v96, v48
	v_fmamk_f32 v48, v48, 0x3c800000, v221
	v_mul_f32_e32 v49, 0x4b800000, v48
	v_cmp_gt_f32_e32 vcc, s55, v48
	s_barrier
	s_nop 0
	v_cndmask_b32_e32 v48, v48, v49, vcc
	v_rsq_f32_e32 v48, v48
	s_add_i32 s26, s25, s20
	s_ashr_i32 s27, s26, 31
	s_lshl_b64 s[26:27], s[26:27], 14
	v_mul_f32_e32 v49, 0x45800000, v48
	v_cndmask_b32_e32 v48, v48, v49, vcc
	v_lshl_add_u64 v[186:187], v[158:159], 0, s[26:27]
	v_lshl_add_u64 v[188:189], v[160:161], 0, s[26:27]
	s_add_u32 s26, s24, s22
	s_addc_u32 s27, s23, 0
	s_mov_b32 s12, 0
	v_lshl_add_u64 v[190:191], v[162:163], 0, s[26:27]
	s_mov_b32 s13, 0
	s_mov_b32 s27, 0
	s_waitcnt vmcnt(2)
	ds_write_b128 v200, v[32:35]
	s_waitcnt vmcnt(1)
	ds_write_b128 v169, v[36:39] offset:17408
	s_waitcnt vmcnt(0)
	ds_write_b128 v203, v[40:43] offset:17408
	v_pk_mul_f32 v[0:1], v[0:1], v[48:49] op_sel_hi:[1,0]
	v_pk_mul_f32 v[28:29], v[28:29], v[48:49] op_sel_hi:[1,0]
	v_pk_mul_f32 v[0:1], v[0:1], v[94:95]
	v_pk_mul_f32 v[2:3], v[2:3], v[48:49] op_sel_hi:[1,0]
	v_pk_mul_f32 v[0:1], v[0:1], s[0:1] op_sel_hi:[1,0]
	v_pk_mul_f32 v[4:5], v[4:5], v[48:49] op_sel_hi:[1,0]
	v_cvt_pk_bf16_f32 v112, v0, v1
	v_pk_mul_f32 v[0:1], v[28:29], v[66:67]
	v_pk_mul_f32 v[6:7], v[6:7], v[48:49] op_sel_hi:[1,0]
	v_pk_mul_f32 v[0:1], v[0:1], s[0:1] op_sel_hi:[1,0]
	v_pk_mul_f32 v[8:9], v[8:9], v[48:49] op_sel_hi:[1,0]
	v_pk_mul_f32 v[10:11], v[10:11], v[48:49] op_sel_hi:[1,0]
	v_pk_mul_f32 v[12:13], v[12:13], v[48:49] op_sel_hi:[1,0]
	v_pk_mul_f32 v[14:15], v[14:15], v[48:49] op_sel_hi:[1,0]
	v_pk_mul_f32 v[16:17], v[16:17], v[48:49] op_sel_hi:[1,0]
	v_pk_mul_f32 v[18:19], v[18:19], v[48:49] op_sel_hi:[1,0]
	v_pk_mul_f32 v[20:21], v[20:21], v[48:49] op_sel_hi:[1,0]
	v_pk_mul_f32 v[22:23], v[22:23], v[48:49] op_sel_hi:[1,0]
	v_pk_mul_f32 v[24:25], v[24:25], v[48:49] op_sel_hi:[1,0]
	v_pk_mul_f32 v[26:27], v[26:27], v[48:49] op_sel_hi:[1,0]
	v_cvt_pk_bf16_f32 v126, v0, v1
	v_pk_mul_f32 v[0:1], v[30:31], v[48:49] op_sel_hi:[1,0]
	v_pk_mul_f32 v[2:3], v[2:3], v[88:89]
	v_pk_mul_f32 v[4:5], v[4:5], v[82:83]
	v_pk_mul_f32 v[6:7], v[6:7], v[76:77]
	v_pk_mul_f32 v[8:9], v[8:9], v[92:93]
	v_pk_mul_f32 v[10:11], v[10:11], v[86:87]
	v_pk_mul_f32 v[12:13], v[12:13], v[80:81]
	v_pk_mul_f32 v[14:15], v[14:15], v[74:75]
	v_pk_mul_f32 v[16:17], v[16:17], v[90:91]
	v_pk_mul_f32 v[18:19], v[18:19], v[84:85]
	v_pk_mul_f32 v[20:21], v[20:21], v[78:79]
	v_pk_mul_f32 v[22:23], v[22:23], v[72:73]
	v_pk_mul_f32 v[24:25], v[24:25], v[70:71]
	v_pk_mul_f32 v[26:27], v[26:27], v[68:69]
	v_pk_mul_f32 v[0:1], v[0:1], v[64:65]
	v_pk_mul_f32 v[2:3], v[2:3], s[0:1] op_sel_hi:[1,0]
	v_pk_mul_f32 v[4:5], v[4:5], s[0:1] op_sel_hi:[1,0]
	v_pk_mul_f32 v[6:7], v[6:7], s[0:1] op_sel_hi:[1,0]
	v_pk_mul_f32 v[8:9], v[8:9], s[0:1] op_sel_hi:[1,0]
	v_pk_mul_f32 v[10:11], v[10:11], s[0:1] op_sel_hi:[1,0]
	v_pk_mul_f32 v[12:13], v[12:13], s[0:1] op_sel_hi:[1,0]
	v_pk_mul_f32 v[14:15], v[14:15], s[0:1] op_sel_hi:[1,0]
	v_pk_mul_f32 v[16:17], v[16:17], s[0:1] op_sel_hi:[1,0]
	v_pk_mul_f32 v[18:19], v[18:19], s[0:1] op_sel_hi:[1,0]
	v_pk_mul_f32 v[20:21], v[20:21], s[0:1] op_sel_hi:[1,0]
	v_pk_mul_f32 v[22:23], v[22:23], s[0:1] op_sel_hi:[1,0]
	v_pk_mul_f32 v[24:25], v[24:25], s[0:1] op_sel_hi:[1,0]
	v_pk_mul_f32 v[26:27], v[26:27], s[0:1] op_sel_hi:[1,0]
	v_pk_mul_f32 v[0:1], v[0:1], s[0:1] op_sel_hi:[1,0]
	s_mov_b32 s0, 0x60000
	v_cvt_pk_bf16_f32 v127, v0, v1
	v_add_co_u32_e32 v0, vcc, s0, v170
	v_cvt_pk_bf16_f32 v113, v2, v3
	s_nop 0
	v_addc_co_u32_e32 v1, vcc, 0, v171, vcc
	global_load_dwordx4 v[128:131], v[0:1], off offset:128
	global_load_dwordx4 v[132:135], v[44:45], off offset:128
	global_load_dwordx4 v[136:139], v[46:47], off offset:128
	v_mov_b32_e32 v0, 0
	v_cvt_pk_bf16_f32 v114, v4, v5
	v_cvt_pk_bf16_f32 v115, v6, v7
	v_cvt_pk_bf16_f32 v116, v8, v9
	v_cvt_pk_bf16_f32 v117, v10, v11
	v_cvt_pk_bf16_f32 v118, v12, v13
	v_cvt_pk_bf16_f32 v119, v14, v15
	v_cvt_pk_bf16_f32 v120, v16, v17
	v_cvt_pk_bf16_f32 v121, v18, v19
	v_cvt_pk_bf16_f32 v122, v20, v21
	v_cvt_pk_bf16_f32 v123, v22, v23
	v_cvt_pk_bf16_f32 v124, v24, v25
	v_cvt_pk_bf16_f32 v125, v26, v27
	s_mov_b64 s[0:1], 0x60000
	v_mov_b32_e32 v1, v0
	v_mov_b32_e32 v2, v0
	v_mov_b32_e32 v3, v0
	v_mov_b32_e32 v4, v0
	v_mov_b32_e32 v5, v0
	v_mov_b32_e32 v6, v0
	v_mov_b32_e32 v7, v0
	v_mov_b32_e32 v8, v0
	v_mov_b32_e32 v9, v0
	v_mov_b32_e32 v10, v0
	v_mov_b32_e32 v11, v0
	v_mov_b32_e32 v12, v0
	v_mov_b32_e32 v13, v0
	v_mov_b32_e32 v14, v0
	v_mov_b32_e32 v15, v0
	v_mov_b32_e32 v16, v0
	v_mov_b32_e32 v17, v0
	v_mov_b32_e32 v18, v0
	v_mov_b32_e32 v19, v0
	v_mov_b32_e32 v20, v0
	v_mov_b32_e32 v21, v0
	v_mov_b32_e32 v22, v0
	v_mov_b32_e32 v23, v0
	v_mov_b32_e32 v24, v0
	v_mov_b32_e32 v25, v0
	v_mov_b32_e32 v26, v0
	v_mov_b32_e32 v27, v0
	v_mov_b32_e32 v28, v0
	v_mov_b32_e32 v29, v0
	v_mov_b32_e32 v30, v0
	v_mov_b32_e32 v31, v0
	v_mov_b32_e32 v32, v0
	v_mov_b32_e32 v33, v0
	v_mov_b32_e32 v34, v0
	v_mov_b32_e32 v35, v0
	v_mov_b32_e32 v36, v0
	v_mov_b32_e32 v37, v0
	v_mov_b32_e32 v38, v0
	v_mov_b32_e32 v39, v0
	v_mov_b32_e32 v40, v0
	v_mov_b32_e32 v41, v0
	v_mov_b32_e32 v42, v0
	v_mov_b32_e32 v43, v0
	v_mov_b32_e32 v44, v0
	v_mov_b32_e32 v45, v0
	v_mov_b32_e32 v46, v0
	v_mov_b32_e32 v47, v0
	v_mov_b32_e32 v48, v0
	v_mov_b32_e32 v49, v0
	v_mov_b32_e32 v50, v0
	v_mov_b32_e32 v51, v0
	v_mov_b32_e32 v52, v0
	v_mov_b32_e32 v53, v0
	v_mov_b32_e32 v54, v0
	v_mov_b32_e32 v55, v0
	v_mov_b32_e32 v56, v0
	v_mov_b32_e32 v57, v0
	v_mov_b32_e32 v58, v0
	v_mov_b32_e32 v59, v0
	v_mov_b32_e32 v60, v0
	v_mov_b32_e32 v61, v0
	v_mov_b32_e32 v62, v0
	v_mov_b32_e32 v63, v0
	v_mov_b32_e32 v64, v0
	v_mov_b32_e32 v65, v0
	v_mov_b32_e32 v66, v0
	v_mov_b32_e32 v67, v0
	v_mov_b32_e32 v68, v0
	v_mov_b32_e32 v69, v0
	v_mov_b32_e32 v70, v0
	v_mov_b32_e32 v71, v0
	v_mov_b32_e32 v72, v0
	v_mov_b32_e32 v73, v0
	v_mov_b32_e32 v74, v0
	v_mov_b32_e32 v75, v0
	v_mov_b32_e32 v76, v0
	v_mov_b32_e32 v77, v0
	v_mov_b32_e32 v78, v0
	v_mov_b32_e32 v79, v0
	s_waitcnt lgkmcnt(0)
	s_barrier
	v_mbcnt_lo_u32_b32 v248, -1, 0
	v_mbcnt_hi_u32_b32 v248, -1, v248
	v_and_b32_e32 v249, 15, v248
	v_bfe_u32 v248, v248, 4, 1
	v_cmp_eq_u32_e32 vcc, v248, v249
	v_mov_b32_e32 v248, s68
	s_nop 1
	v_cndmask_b32_e32 v226, 0, v248, vcc
	v_cndmask_b32_e32 v227, 0, v248, vcc
	v_cndmask_b32_e32 v228, 0, v248, vcc
	v_cndmask_b32_e32 v229, 0, v248, vcc
	v_mov_b32_e32 v248, 0
	v_mov_b32_e32 v249, 0
	v_mov_b32_e32 v250, 0
	v_mov_b32_e32 v251, 0
	s_branch .LBB0_1037

.Lfar_p1:
	v_add_u32_e32 v175, s27, v198
	ds_read_b128 v[178:181], v175
	ds_read_b128 v[206:209], v175 offset:32
	ds_read_b128 v[210:213], v175 offset:64
	ds_read_b128 v[214:217], v175 offset:96
	ds_read_b128 v[230:233], v175 offset:4608
	ds_read_b128 v[236:239], v175 offset:4640
	s_cmp_gt_i32 s30, -1
	s_cselect_b64 vcc, -1, 0
	s_nop 1
	v_cndmask_b32_e32 v80, v204, v205, vcc
	v_mov_b32_e32 v81, v80
	v_mov_b32_e32 v82, v80
	v_mov_b32_e32 v83, v80
	v_mov_b32_e32 v84, v80
	v_mov_b32_e32 v85, v80
	v_mov_b32_e32 v86, v80
	v_mov_b32_e32 v87, v80
	v_mov_b32_e32 v88, v80
	v_mov_b32_e32 v89, v80
	v_mov_b32_e32 v90, v80
	v_mov_b32_e32 v91, v80
	v_mov_b32_e32 v92, v80
	v_mov_b32_e32 v93, v80
	v_mov_b32_e32 v94, v80
	v_mov_b32_e32 v95, v80
	s_nop 0
.Lfar_p1_main:
	s_waitcnt lgkmcnt(5)
	v_mfma_f32_32x32x16_bf16 v[96:111], v[178:181], v[112:115], v[80:95]
	ds_read_b128 v[178:181], v175 offset:4672
	s_waitcnt lgkmcnt(5)
	v_mfma_f32_32x32x16_bf16 v[96:111], v[206:209], v[116:119], v[96:111]
	ds_read_b128 v[206:209], v175 offset:4704
	s_waitcnt lgkmcnt(5)
	v_mfma_f32_32x32x16_bf16 v[96:111], v[210:213], v[120:123], v[96:111]
	ds_read_b128 v[210:213], v175 offset:17408
	s_waitcnt lgkmcnt(5)
	v_mfma_f32_32x32x16_bf16 v[96:111], v[214:217], v[124:127], v[96:111]
	ds_read_b128 v[214:217], v175 offset:22016
	s_waitcnt lgkmcnt(5)
	v_mfma_f32_32x32x16_bf16 v[80:95], v[230:233], v[112:115], v[80:95]
	ds_read_b128 v[230:233], v175 offset:26624
	s_waitcnt lgkmcnt(5)
	v_mfma_f32_32x32x16_bf16 v[80:95], v[236:239], v[116:119], v[80:95]
	ds_read_b128 v[236:239], v175 offset:31232
	v_add_u32_e32 v185, s26, v194
	v_add3_u32 v184, s26, v192, v193
	v_add_u32_e32 v218, v185, v197
	v_add_u32_e32 v185, v185, v196
	s_nop 0
	v_exp_f32_e32 v96, v96
	v_exp_f32_e32 v97, v97
	v_exp_f32_e32 v98, v98
	s_waitcnt lgkmcnt(5)
	v_mfma_f32_32x32x16_bf16 v[80:95], v[178:181], v[120:123], v[80:95]
	ds_read_b128 v[178:181], v175 offset:17440
	v_exp_f32_e32 v99, v99
	v_exp_f32_e32 v100, v100
	v_exp_f32_e32 v101, v101
	s_waitcnt lgkmcnt(5)
	v_mfma_f32_32x32x16_bf16 v[80:95], v[206:209], v[124:127], v[80:95]
	ds_read_b128 v[206:209], v175 offset:22048
	v_exp_f32_e32 v102, v102
	v_exp_f32_e32 v103, v103
	v_cvt_pk_bf16_f32 v96, v96, v97
	v_cvt_pk_bf16_f32 v97, v98, v99
	v_cvt_pk_bf16_f32 v98, v100, v101
	v_cvt_pk_bf16_f32 v99, v102, v103
	s_nop 1
	v_mfma_f32_16x16x32_bf16 v[248:251], v[226:229], v[96:99], v[248:251]
	v_exp_f32_e32 v104, v104
	v_exp_f32_e32 v105, v105
	v_exp_f32_e32 v106, v106
	s_waitcnt lgkmcnt(5)
	v_mfma_f32_32x32x16_bf16 v[48:63], v[210:213], v[96:99], v[48:63]
	ds_read_b128 v[210:213], v175 offset:26656
	s_waitcnt vmcnt(2)
	ds_write_b128 v184, v[128:131]
	v_exp_f32_e32 v107, v107
	v_exp_f32_e32 v108, v108
	v_exp_f32_e32 v109, v109
	s_waitcnt lgkmcnt(6)
	v_mfma_f32_32x32x16_bf16 v[32:47], v[214:217], v[96:99], v[32:47]
	ds_read_b128 v[214:217], v175 offset:31264
	s_waitcnt vmcnt(1)
	ds_write_b128 v185, v[132:135] offset:17408
	v_exp_f32_e32 v110, v110
	v_exp_f32_e32 v111, v111
	v_cvt_pk_bf16_f32 v104, v104, v105
	s_waitcnt lgkmcnt(7)
	v_mfma_f32_32x32x16_bf16 v[16:31], v[230:233], v[96:99], v[16:31]
	ds_read_b128 v[230:233], v175 offset:17472
	s_waitcnt vmcnt(0)
	ds_write_b128 v218, v[136:139] offset:17408
	v_cvt_pk_bf16_f32 v105, v106, v107
	v_cvt_pk_bf16_f32 v106, v108, v109
	v_cvt_pk_bf16_f32 v107, v110, v111
	s_waitcnt lgkmcnt(8)
	v_mfma_f32_32x32x16_bf16 v[0:15], v[236:239], v[96:99], v[0:15]
	ds_read_b128 v[236:239], v175 offset:22080
	v_mfma_f32_16x16x32_bf16 v[248:251], v[226:229], v[104:107], v[248:251]
	v_exp_f32_e32 v80, v80
	v_exp_f32_e32 v81, v81
	v_exp_f32_e32 v82, v82
	s_waitcnt lgkmcnt(8)
	v_mfma_f32_32x32x16_bf16 v[48:63], v[178:181], v[104:107], v[48:63]
	ds_read_b128 v[178:181], v175 offset:26688
	v_exp_f32_e32 v83, v83
	v_exp_f32_e32 v84, v84
	v_exp_f32_e32 v85, v85
	s_waitcnt lgkmcnt(8)
	v_mfma_f32_32x32x16_bf16 v[32:47], v[206:209], v[104:107], v[32:47]
	ds_read_b128 v[206:209], v175 offset:31296
	v_exp_f32_e32 v86, v86
	v_exp_f32_e32 v87, v87
	v_cvt_pk_bf16_f32 v80, v80, v81
	s_waitcnt lgkmcnt(8)
	v_mfma_f32_32x32x16_bf16 v[16:31], v[210:213], v[104:107], v[16:31]
	ds_read_b128 v[210:213], v175 offset:17504
	v_cvt_pk_bf16_f32 v81, v82, v83
	v_cvt_pk_bf16_f32 v82, v84, v85
	v_cvt_pk_bf16_f32 v83, v86, v87
	s_waitcnt lgkmcnt(7)
	v_mfma_f32_32x32x16_bf16 v[0:15], v[214:217], v[104:107], v[0:15]
	ds_read_b128 v[214:217], v175 offset:22112
	s_waitcnt lgkmcnt(5)
	s_barrier
	s_add_i32 s28, s12, 64
	s_cmpk_eq_i32 s28, 0x2000
	s_cbranch_scc1 .Lfar_p1_tailnp
	s_add_i32 s30, s21, s28
	s_addk_i32 s30, 0x99
	s_cmpk_gt_u32 s30, 0x112
	s_cbranch_scc0 .Lfar_p1_tailnp
	v_mfma_f32_16x16x32_bf16 v[248:251], v[226:229], v[80:83], v[248:251]
	v_exp_f32_e32 v88, v88
	v_exp_f32_e32 v89, v89
	v_exp_f32_e32 v90, v90
	v_mfma_f32_32x32x16_bf16 v[48:63], v[230:233], v[80:83], v[48:63]
	ds_read_b128 v[230:233], v175 offset:26720
	v_exp_f32_e32 v91, v91
	v_exp_f32_e32 v92, v92
	v_exp_f32_e32 v93, v93
	s_waitcnt lgkmcnt(5)
	v_mfma_f32_32x32x16_bf16 v[32:47], v[236:239], v[80:83], v[32:47]
	ds_read_b128 v[236:239], v175 offset:31328
	s_cmpk_gt_u32 s13, 0x7d
	s_cbranch_scc1 .Lfar_p1_noloada
	global_load_dwordx4 v[128:131], v[190:191], off
	global_load_dwordx4 v[132:135], v[188:189], off
	global_load_dwordx4 v[136:139], v[186:187], off
.Lfar_p1_noloada:
	v_exp_f32_e32 v94, v94
	v_exp_f32_e32 v95, v95
	v_cvt_pk_bf16_f32 v88, v88, v89
	s_waitcnt lgkmcnt(5)
	v_mfma_f32_32x32x16_bf16 v[16:31], v[178:181], v[80:83], v[16:31]
	v_add_u32_e32 v175, s26, v198
	ds_read_b128 v[178:181], v175
	v_cvt_pk_bf16_f32 v89, v90, v91
	v_cvt_pk_bf16_f32 v90, v92, v93
	v_cvt_pk_bf16_f32 v91, v94, v95
	s_waitcnt lgkmcnt(5)
	v_mfma_f32_32x32x16_bf16 v[0:15], v[206:209], v[80:83], v[0:15]
	ds_read_b128 v[206:209], v175 offset:32
	v_mfma_f32_16x16x32_bf16 v[248:251], v[226:229], v[88:91], v[248:251]
	s_add_i32 s12, s12, 64
	s_add_i32 s13, s13, 1
	s_waitcnt lgkmcnt(5)
	v_mfma_f32_32x32x16_bf16 v[48:63], v[210:213], v[88:91], v[48:63]
	ds_read_b128 v[210:213], v175 offset:64
	v_lshl_add_u64 v[186:187], v[186:187], 0, s[72:73]
	s_waitcnt lgkmcnt(5)
	v_mfma_f32_32x32x16_bf16 v[32:47], v[214:217], v[88:91], v[32:47]
	ds_read_b128 v[214:217], v175 offset:96
	v_lshl_add_u64 v[188:189], v[188:189], 0, s[72:73]
	s_waitcnt lgkmcnt(5)
	v_mfma_f32_32x32x16_bf16 v[16:31], v[230:233], v[88:91], v[16:31]
	ds_read_b128 v[230:233], v175 offset:4608
	v_lshl_add_u64 v[190:191], v[190:191], 0, s[0:1]
	s_mov_b32 s27, s26
	s_waitcnt lgkmcnt(5)
	v_mfma_f32_32x32x16_bf16 v[0:15], v[236:239], v[88:91], v[0:15]
	ds_read_b128 v[236:239], v175 offset:4640
	s_add_i32 s26, s27, 0x8c00
	s_cmp_lg_u32 s27, 0x11800
	s_cselect_b32 s26, s26, 0
	s_cmp_gt_i32 s30, -1
	s_cselect_b64 vcc, -1, 0
	s_nop 1
	v_cndmask_b32_e32 v80, v204, v205, vcc
	v_mov_b32_e32 v81, v80
	v_mov_b32_e32 v82, v80
	v_mov_b32_e32 v83, v80
	v_mov_b32_e32 v84, v80
	v_mov_b32_e32 v85, v80
	v_mov_b32_e32 v86, v80
	v_mov_b32_e32 v87, v80
	v_mov_b32_e32 v88, v80
	v_mov_b32_e32 v89, v80
	v_mov_b32_e32 v90, v80
	v_mov_b32_e32 v91, v80
	v_mov_b32_e32 v92, v80
	v_mov_b32_e32 v93, v80
	v_mov_b32_e32 v94, v80
	v_mov_b32_e32 v95, v80
	s_nop 0
	s_branch .Lfar_p1_main
.Lfar_p1_tailnp:
	v_mfma_f32_16x16x32_bf16 v[248:251], v[226:229], v[80:83], v[248:251]
	v_exp_f32_e32 v88, v88
	v_exp_f32_e32 v89, v89
	v_exp_f32_e32 v90, v90
	v_mfma_f32_32x32x16_bf16 v[48:63], v[230:233], v[80:83], v[48:63]
	ds_read_b128 v[230:233], v175 offset:26720
	v_exp_f32_e32 v91, v91
	v_exp_f32_e32 v92, v92
	v_exp_f32_e32 v93, v93
	s_waitcnt lgkmcnt(5)
	v_mfma_f32_32x32x16_bf16 v[32:47], v[236:239], v[80:83], v[32:47]
	ds_read_b128 v[236:239], v175 offset:31328
	s_cmpk_gt_u32 s13, 0x7d
	s_cbranch_scc1 .Lfar_p1_noloadb
	global_load_dwordx4 v[128:131], v[190:191], off
	global_load_dwordx4 v[132:135], v[188:189], off
	global_load_dwordx4 v[136:139], v[186:187], off
.Lfar_p1_noloadb:
	v_exp_f32_e32 v94, v94
	v_exp_f32_e32 v95, v95
	v_cvt_pk_bf16_f32 v88, v88, v89
	s_waitcnt lgkmcnt(5)
	v_mfma_f32_32x32x16_bf16 v[16:31], v[178:181], v[80:83], v[16:31]
	v_cvt_pk_bf16_f32 v89, v90, v91
	v_cvt_pk_bf16_f32 v90, v92, v93
	v_cvt_pk_bf16_f32 v91, v94, v95
	s_waitcnt lgkmcnt(4)
	v_mfma_f32_32x32x16_bf16 v[0:15], v[206:209], v[80:83], v[0:15]
	v_mfma_f32_16x16x32_bf16 v[248:251], v[226:229], v[88:91], v[248:251]
	s_add_i32 s12, s12, 64
	s_add_i32 s13, s13, 1
	s_waitcnt lgkmcnt(3)
	v_mfma_f32_32x32x16_bf16 v[48:63], v[210:213], v[88:91], v[48:63]
	v_lshl_add_u64 v[186:187], v[186:187], 0, s[72:73]
	s_waitcnt lgkmcnt(2)
	v_mfma_f32_32x32x16_bf16 v[32:47], v[214:217], v[88:91], v[32:47]
	v_lshl_add_u64 v[188:189], v[188:189], 0, s[72:73]
	s_waitcnt lgkmcnt(1)
	v_mfma_f32_32x32x16_bf16 v[16:31], v[230:233], v[88:91], v[16:31]
	v_lshl_add_u64 v[190:191], v[190:191], 0, s[0:1]
	s_mov_b32 s27, s26
	s_waitcnt lgkmcnt(0)
	v_mfma_f32_32x32x16_bf16 v[0:15], v[236:239], v[88:91], v[0:15]
	s_cmpk_lg_i32 s12, 0x2000
	s_cbranch_scc0 .LBB0_1043
	s_branch .LBB0_1037

.LBB0_1056:
.LBB0_1057:
	s_andn2_saveexec_b64 s[4:5], s[12:13]
	s_cbranch_execz .LBB0_1020
	v_mbcnt_lo_u32_b32 v36, -1, 0
	v_mbcnt_hi_u32_b32 v36, -1, v36
	s_nop 8
	global_load_dwordx4 v[0:3], v[144:145], off
	global_load_dwordx4 v[4:7], v[144:145], off offset:16
	global_load_dwordx4 v[8:11], v[144:145], off offset:64
	global_load_dwordx4 v[12:15], v[144:145], off offset:80
	global_load_dwordx4 v[16:19], v[144:145], off offset:128
	global_load_dwordx4 v[20:23], v[144:145], off offset:144
	global_load_dwordx4 v[24:27], v[144:145], off offset:192
	global_load_dwordx4 v[28:31], v[144:145], off offset:208
	global_load_dwordx4 v[32:35], v[170:171], off
	v_mov_b32_e32 v175, v177
	v_lshlrev_b32_e32 v38, 2, v36
	v_lshl_add_u64 v[36:37], s[10:11], 0, v[174:175]
	v_xor_b32_e32 v38, 0x80, v38
	v_lshl_add_u64 v[44:45], v[36:37], 0, v[152:153]
	s_waitcnt vmcnt(0)
	ds_bpermute_b32 v48, v38, v96
	v_lshl_add_u64 v[46:47], v[36:37], 0, v[154:155]
	global_load_dwordx4 v[36:39], v[44:45], off
	global_load_dwordx4 v[40:43], v[46:47], off
	s_mov_b32 s0, 0x3e38aa3b
	s_waitcnt lgkmcnt(0)
	v_add_f32_e32 v48, v96, v48
	v_fmamk_f32 v48, v48, 0x3c800000, v221
	v_mul_f32_e32 v49, 0x4b800000, v48
	v_cmp_gt_f32_e32 vcc, s55, v48
	s_barrier
	s_nop 0
	v_cndmask_b32_e32 v48, v48, v49, vcc
	v_rsq_f32_e32 v48, v48
	s_add_i32 s12, s25, s20
	s_ashr_i32 s13, s12, 31
	s_lshl_b64 s[12:13], s[12:13], 14
	v_mul_f32_e32 v49, 0x45800000, v48
	v_cndmask_b32_e32 v48, v48, v49, vcc
	v_lshl_add_u64 v[172:173], v[160:161], 0, s[12:13]
	s_mov_b32 s10, 0
	s_mov_b32 s11, 0
	ds_write_b128 v200, v[32:35]
	s_waitcnt vmcnt(1)
	ds_write_b128 v169, v[36:39] offset:17408
	s_waitcnt vmcnt(0)
	ds_write_b128 v203, v[40:43] offset:17408
	v_pk_mul_f32 v[0:1], v[0:1], v[48:49] op_sel_hi:[1,0]
	v_pk_mul_f32 v[28:29], v[28:29], v[48:49] op_sel_hi:[1,0]
	v_pk_mul_f32 v[0:1], v[0:1], v[68:69]
	v_pk_mul_f32 v[2:3], v[2:3], v[48:49] op_sel_hi:[1,0]
	v_pk_mul_f32 v[0:1], v[0:1], s[0:1] op_sel_hi:[1,0]
	v_pk_mul_f32 v[4:5], v[4:5], v[48:49] op_sel_hi:[1,0]
	v_cvt_pk_bf16_f32 v112, v0, v1
	v_pk_mul_f32 v[0:1], v[28:29], v[66:67]
	v_pk_mul_f32 v[6:7], v[6:7], v[48:49] op_sel_hi:[1,0]
	v_pk_mul_f32 v[0:1], v[0:1], s[0:1] op_sel_hi:[1,0]
	v_pk_mul_f32 v[8:9], v[8:9], v[48:49] op_sel_hi:[1,0]
	v_pk_mul_f32 v[10:11], v[10:11], v[48:49] op_sel_hi:[1,0]
	v_pk_mul_f32 v[12:13], v[12:13], v[48:49] op_sel_hi:[1,0]
	v_pk_mul_f32 v[14:15], v[14:15], v[48:49] op_sel_hi:[1,0]
	v_pk_mul_f32 v[16:17], v[16:17], v[48:49] op_sel_hi:[1,0]
	v_pk_mul_f32 v[18:19], v[18:19], v[48:49] op_sel_hi:[1,0]
	v_pk_mul_f32 v[20:21], v[20:21], v[48:49] op_sel_hi:[1,0]
	v_pk_mul_f32 v[22:23], v[22:23], v[48:49] op_sel_hi:[1,0]
	v_pk_mul_f32 v[24:25], v[24:25], v[48:49] op_sel_hi:[1,0]
	v_pk_mul_f32 v[26:27], v[26:27], v[48:49] op_sel_hi:[1,0]
	v_cvt_pk_bf16_f32 v126, v0, v1
	v_pk_mul_f32 v[0:1], v[30:31], v[48:49] op_sel_hi:[1,0]
	v_pk_mul_f32 v[2:3], v[2:3], v[70:71]
	v_pk_mul_f32 v[4:5], v[4:5], v[72:73]
	v_pk_mul_f32 v[6:7], v[6:7], v[74:75]
	v_pk_mul_f32 v[8:9], v[8:9], v[80:81]
	v_pk_mul_f32 v[10:11], v[10:11], v[82:83]
	v_pk_mul_f32 v[12:13], v[12:13], v[84:85]
	v_pk_mul_f32 v[14:15], v[14:15], v[86:87]
	v_pk_mul_f32 v[16:17], v[16:17], v[88:89]
	v_pk_mul_f32 v[18:19], v[18:19], v[90:91]
	v_pk_mul_f32 v[20:21], v[20:21], v[92:93]
	v_pk_mul_f32 v[22:23], v[22:23], v[94:95]
	v_pk_mul_f32 v[24:25], v[24:25], v[78:79]
	v_pk_mul_f32 v[26:27], v[26:27], v[76:77]
	v_pk_mul_f32 v[0:1], v[0:1], v[64:65]
	v_pk_mul_f32 v[2:3], v[2:3], s[0:1] op_sel_hi:[1,0]
	v_pk_mul_f32 v[4:5], v[4:5], s[0:1] op_sel_hi:[1,0]
	v_pk_mul_f32 v[6:7], v[6:7], s[0:1] op_sel_hi:[1,0]
	v_pk_mul_f32 v[8:9], v[8:9], s[0:1] op_sel_hi:[1,0]
	v_pk_mul_f32 v[10:11], v[10:11], s[0:1] op_sel_hi:[1,0]
	v_pk_mul_f32 v[12:13], v[12:13], s[0:1] op_sel_hi:[1,0]
	v_pk_mul_f32 v[14:15], v[14:15], s[0:1] op_sel_hi:[1,0]
	v_pk_mul_f32 v[16:17], v[16:17], s[0:1] op_sel_hi:[1,0]
	v_pk_mul_f32 v[18:19], v[18:19], s[0:1] op_sel_hi:[1,0]
	v_pk_mul_f32 v[20:21], v[20:21], s[0:1] op_sel_hi:[1,0]
	v_pk_mul_f32 v[22:23], v[22:23], s[0:1] op_sel_hi:[1,0]
	v_pk_mul_f32 v[24:25], v[24:25], s[0:1] op_sel_hi:[1,0]
	v_pk_mul_f32 v[26:27], v[26:27], s[0:1] op_sel_hi:[1,0]
	v_pk_mul_f32 v[0:1], v[0:1], s[0:1] op_sel_hi:[1,0]
	s_mov_b32 s0, 0x60000
	v_cvt_pk_bf16_f32 v127, v0, v1
	v_add_co_u32_e32 v0, vcc, s0, v170
	v_cvt_pk_bf16_f32 v113, v2, v3
	s_nop 0
	v_addc_co_u32_e32 v1, vcc, 0, v171, vcc
	global_load_dwordx4 v[128:131], v[0:1], off
	global_load_dwordx4 v[132:135], v[44:45], off offset:128
	global_load_dwordx4 v[136:139], v[46:47], off offset:128
	v_lshl_add_u64 v[170:171], v[158:159], 0, s[12:13]
	s_add_u32 s12, s24, s22
	s_addc_u32 s13, s23, 0
	v_mov_b32_e32 v0, 0
	v_cvt_pk_bf16_f32 v114, v4, v5
	v_cvt_pk_bf16_f32 v115, v6, v7
	v_cvt_pk_bf16_f32 v116, v8, v9
	v_cvt_pk_bf16_f32 v117, v10, v11
	v_cvt_pk_bf16_f32 v118, v12, v13
	v_cvt_pk_bf16_f32 v119, v14, v15
	v_cvt_pk_bf16_f32 v120, v16, v17
	v_cvt_pk_bf16_f32 v121, v18, v19
	v_cvt_pk_bf16_f32 v122, v20, v21
	v_cvt_pk_bf16_f32 v123, v22, v23
	v_cvt_pk_bf16_f32 v124, v24, v25
	v_cvt_pk_bf16_f32 v125, v26, v27
	s_mov_b64 s[0:1], 0x60000
	v_lshl_add_u64 v[174:175], v[164:165], 0, s[12:13]
	s_mov_b32 s13, 0
	v_mov_b32_e32 v1, v0
	v_mov_b32_e32 v2, v0
	v_mov_b32_e32 v3, v0
	v_mov_b32_e32 v4, v0
	v_mov_b32_e32 v5, v0
	v_mov_b32_e32 v6, v0
	v_mov_b32_e32 v7, v0
	v_mov_b32_e32 v8, v0
	v_mov_b32_e32 v9, v0
	v_mov_b32_e32 v10, v0
	v_mov_b32_e32 v11, v0
	v_mov_b32_e32 v12, v0
	v_mov_b32_e32 v13, v0
	v_mov_b32_e32 v14, v0
	v_mov_b32_e32 v15, v0
	v_mov_b32_e32 v16, v0
	v_mov_b32_e32 v17, v0
	v_mov_b32_e32 v18, v0
	v_mov_b32_e32 v19, v0
	v_mov_b32_e32 v20, v0
	v_mov_b32_e32 v21, v0
	v_mov_b32_e32 v22, v0
	v_mov_b32_e32 v23, v0
	v_mov_b32_e32 v24, v0
	v_mov_b32_e32 v25, v0
	v_mov_b32_e32 v26, v0
	v_mov_b32_e32 v27, v0
	v_mov_b32_e32 v28, v0
	v_mov_b32_e32 v29, v0
	v_mov_b32_e32 v30, v0
	v_mov_b32_e32 v31, v0
	v_mov_b32_e32 v32, v0
	v_mov_b32_e32 v33, v0
	v_mov_b32_e32 v34, v0
	v_mov_b32_e32 v35, v0
	v_mov_b32_e32 v36, v0
	v_mov_b32_e32 v37, v0
	v_mov_b32_e32 v38, v0
	v_mov_b32_e32 v39, v0
	v_mov_b32_e32 v40, v0
	v_mov_b32_e32 v41, v0
	v_mov_b32_e32 v42, v0
	v_mov_b32_e32 v43, v0
	v_mov_b32_e32 v44, v0
	v_mov_b32_e32 v45, v0
	v_mov_b32_e32 v46, v0
	v_mov_b32_e32 v47, v0
	v_mov_b32_e32 v48, v0
	v_mov_b32_e32 v49, v0
	v_mov_b32_e32 v50, v0
	v_mov_b32_e32 v51, v0
	v_mov_b32_e32 v52, v0
	v_mov_b32_e32 v53, v0
	v_mov_b32_e32 v54, v0
	v_mov_b32_e32 v55, v0
	v_mov_b32_e32 v56, v0
	v_mov_b32_e32 v57, v0
	v_mov_b32_e32 v58, v0
	v_mov_b32_e32 v59, v0
	v_mov_b32_e32 v60, v0
	v_mov_b32_e32 v61, v0
	v_mov_b32_e32 v62, v0
	v_mov_b32_e32 v63, v0
	v_mov_b32_e32 v64, v0
	v_mov_b32_e32 v65, v0
	v_mov_b32_e32 v66, v0
	v_mov_b32_e32 v67, v0
	v_mov_b32_e32 v68, v0
	v_mov_b32_e32 v69, v0
	v_mov_b32_e32 v70, v0
	v_mov_b32_e32 v71, v0
	v_mov_b32_e32 v72, v0
	v_mov_b32_e32 v73, v0
	v_mov_b32_e32 v74, v0
	v_mov_b32_e32 v75, v0
	v_mov_b32_e32 v76, v0
	v_mov_b32_e32 v77, v0
	v_mov_b32_e32 v78, v0
	v_mov_b32_e32 v79, v0
	s_waitcnt lgkmcnt(0)
	s_barrier
	v_mbcnt_lo_u32_b32 v248, -1, 0
	v_mbcnt_hi_u32_b32 v248, -1, v248
	v_and_b32_e32 v249, 15, v248
	v_bfe_u32 v248, v248, 4, 1
	v_cmp_eq_u32_e32 vcc, v248, v249
	v_mov_b32_e32 v248, s68
	s_nop 1
	v_cndmask_b32_e32 v226, 0, v248, vcc
	v_cndmask_b32_e32 v227, 0, v248, vcc
	v_cndmask_b32_e32 v228, 0, v248, vcc
	v_cndmask_b32_e32 v229, 0, v248, vcc
	v_mov_b32_e32 v248, 0
	v_mov_b32_e32 v249, 0
	v_mov_b32_e32 v250, 0
	v_mov_b32_e32 v251, 0
	s_branch .LBB0_1060

.Lfar_p2:
	v_add_u32_e32 v169, s13, v198
	ds_read_b128 v[178:181], v169
	ds_read_b128 v[206:209], v169 offset:32
	ds_read_b128 v[210:213], v169 offset:64
	ds_read_b128 v[214:217], v169 offset:96
	ds_read_b128 v[230:233], v169 offset:4608
	ds_read_b128 v[236:239], v169 offset:4640
	s_cmp_gt_i32 s24, -1
	s_cselect_b64 vcc, -1, 0
	s_nop 1
	v_cndmask_b32_e32 v80, v204, v205, vcc
	v_mov_b32_e32 v81, v80
	v_mov_b32_e32 v82, v80
	v_mov_b32_e32 v83, v80
	v_mov_b32_e32 v84, v80
	v_mov_b32_e32 v85, v80
	v_mov_b32_e32 v86, v80
	v_mov_b32_e32 v87, v80
	v_mov_b32_e32 v88, v80
	v_mov_b32_e32 v89, v80
	v_mov_b32_e32 v90, v80
	v_mov_b32_e32 v91, v80
	v_mov_b32_e32 v92, v80
	v_mov_b32_e32 v93, v80
	v_mov_b32_e32 v94, v80
	v_mov_b32_e32 v95, v80
	s_nop 0
.Lfar_p2_main:
	s_waitcnt lgkmcnt(5)
	v_mfma_f32_32x32x16_bf16 v[96:111], v[178:181], v[112:115], v[80:95]
	ds_read_b128 v[178:181], v169 offset:4672
	s_waitcnt lgkmcnt(5)
	v_mfma_f32_32x32x16_bf16 v[96:111], v[206:209], v[116:119], v[96:111]
	ds_read_b128 v[206:209], v169 offset:4704
	s_waitcnt lgkmcnt(5)
	v_mfma_f32_32x32x16_bf16 v[96:111], v[210:213], v[120:123], v[96:111]
	ds_read_b128 v[210:213], v169 offset:17408
	s_waitcnt lgkmcnt(5)
	v_mfma_f32_32x32x16_bf16 v[96:111], v[214:217], v[124:127], v[96:111]
	ds_read_b128 v[214:217], v169 offset:22016
	s_waitcnt lgkmcnt(5)
	v_mfma_f32_32x32x16_bf16 v[80:95], v[230:233], v[112:115], v[80:95]
	ds_read_b128 v[230:233], v169 offset:26624
	s_waitcnt lgkmcnt(5)
	v_mfma_f32_32x32x16_bf16 v[80:95], v[236:239], v[116:119], v[80:95]
	ds_read_b128 v[236:239], v169 offset:31232
	v_add_u32_e32 v185, s12, v194
	v_add3_u32 v184, s12, v192, v193
	v_add_u32_e32 v218, v185, v197
	v_add_u32_e32 v185, v185, v196
	s_nop 0
	v_exp_f32_e32 v96, v96
	v_exp_f32_e32 v97, v97
	v_exp_f32_e32 v98, v98
	s_waitcnt lgkmcnt(5)
	v_mfma_f32_32x32x16_bf16 v[80:95], v[178:181], v[120:123], v[80:95]
	ds_read_b128 v[178:181], v169 offset:17440
	v_exp_f32_e32 v99, v99
	v_exp_f32_e32 v100, v100
	v_exp_f32_e32 v101, v101
	s_waitcnt lgkmcnt(5)
	v_mfma_f32_32x32x16_bf16 v[80:95], v[206:209], v[124:127], v[80:95]
	ds_read_b128 v[206:209], v169 offset:22048
	v_exp_f32_e32 v102, v102
	v_exp_f32_e32 v103, v103
	v_cvt_pk_bf16_f32 v96, v96, v97
	v_cvt_pk_bf16_f32 v97, v98, v99
	v_cvt_pk_bf16_f32 v98, v100, v101
	v_cvt_pk_bf16_f32 v99, v102, v103
	s_nop 1
	v_mfma_f32_16x16x32_bf16 v[248:251], v[226:229], v[96:99], v[248:251]
	v_exp_f32_e32 v104, v104
	v_exp_f32_e32 v105, v105
	v_exp_f32_e32 v106, v106
	s_waitcnt lgkmcnt(5)
	v_mfma_f32_32x32x16_bf16 v[48:63], v[210:213], v[96:99], v[48:63]
	ds_read_b128 v[210:213], v169 offset:26656
	s_waitcnt vmcnt(2)
	ds_write_b128 v184, v[128:131]
	v_exp_f32_e32 v107, v107
	v_exp_f32_e32 v108, v108
	v_exp_f32_e32 v109, v109
	s_waitcnt lgkmcnt(6)
	v_mfma_f32_32x32x16_bf16 v[32:47], v[214:217], v[96:99], v[32:47]
	ds_read_b128 v[214:217], v169 offset:31264
	s_waitcnt vmcnt(1)
	ds_write_b128 v185, v[132:135] offset:17408
	v_exp_f32_e32 v110, v110
	v_exp_f32_e32 v111, v111
	v_cvt_pk_bf16_f32 v104, v104, v105
	s_waitcnt lgkmcnt(7)
	v_mfma_f32_32x32x16_bf16 v[16:31], v[230:233], v[96:99], v[16:31]
	ds_read_b128 v[230:233], v169 offset:17472
	s_waitcnt vmcnt(0)
	ds_write_b128 v218, v[136:139] offset:17408
	v_cvt_pk_bf16_f32 v105, v106, v107
	v_cvt_pk_bf16_f32 v106, v108, v109
	v_cvt_pk_bf16_f32 v107, v110, v111
	s_waitcnt lgkmcnt(8)
	v_mfma_f32_32x32x16_bf16 v[0:15], v[236:239], v[96:99], v[0:15]
	ds_read_b128 v[236:239], v169 offset:22080
	v_mfma_f32_16x16x32_bf16 v[248:251], v[226:229], v[104:107], v[248:251]
	v_exp_f32_e32 v80, v80
	v_exp_f32_e32 v81, v81
	v_exp_f32_e32 v82, v82
	s_waitcnt lgkmcnt(8)
	v_mfma_f32_32x32x16_bf16 v[48:63], v[178:181], v[104:107], v[48:63]
	ds_read_b128 v[178:181], v169 offset:26688
	v_exp_f32_e32 v83, v83
	v_exp_f32_e32 v84, v84
	v_exp_f32_e32 v85, v85
	s_waitcnt lgkmcnt(8)
	v_mfma_f32_32x32x16_bf16 v[32:47], v[206:209], v[104:107], v[32:47]
	ds_read_b128 v[206:209], v169 offset:31296
	v_exp_f32_e32 v86, v86
	v_exp_f32_e32 v87, v87
	v_cvt_pk_bf16_f32 v80, v80, v81
	s_waitcnt lgkmcnt(8)
	v_mfma_f32_32x32x16_bf16 v[16:31], v[210:213], v[104:107], v[16:31]
	ds_read_b128 v[210:213], v169 offset:17504
	v_cvt_pk_bf16_f32 v81, v82, v83
	v_cvt_pk_bf16_f32 v82, v84, v85
	v_cvt_pk_bf16_f32 v83, v86, v87
	s_waitcnt lgkmcnt(7)
	v_mfma_f32_32x32x16_bf16 v[0:15], v[214:217], v[104:107], v[0:15]
	ds_read_b128 v[214:217], v169 offset:22112
	s_waitcnt lgkmcnt(5)
	s_barrier
	s_add_i32 s22, s10, 64
	s_cmpk_eq_i32 s22, 0x2000
	s_cbranch_scc1 .Lfar_p2_tailnp
	s_add_i32 s24, s21, s22
	s_addk_i32 s24, 0x99
	s_cmpk_gt_u32 s24, 0x112
	s_cbranch_scc0 .Lfar_p2_tailnp
	v_mfma_f32_16x16x32_bf16 v[248:251], v[226:229], v[80:83], v[248:251]
	v_exp_f32_e32 v88, v88
	v_exp_f32_e32 v89, v89
	v_exp_f32_e32 v90, v90
	v_mfma_f32_32x32x16_bf16 v[48:63], v[230:233], v[80:83], v[48:63]
	ds_read_b128 v[230:233], v169 offset:26720
	v_exp_f32_e32 v91, v91
	v_exp_f32_e32 v92, v92
	v_exp_f32_e32 v93, v93
	s_waitcnt lgkmcnt(5)
	v_mfma_f32_32x32x16_bf16 v[32:47], v[236:239], v[80:83], v[32:47]
	ds_read_b128 v[236:239], v169 offset:31328
	s_cmpk_gt_u32 s11, 0x7d
	s_cbranch_scc1 .Lfar_p2_noloada
	global_load_dwordx4 v[128:131], v[174:175], off
	global_load_dwordx4 v[132:135], v[172:173], off
	global_load_dwordx4 v[136:139], v[170:171], off
.Lfar_p2_noloada:
	v_exp_f32_e32 v94, v94
	v_exp_f32_e32 v95, v95
	v_cvt_pk_bf16_f32 v88, v88, v89
	s_waitcnt lgkmcnt(5)
	v_mfma_f32_32x32x16_bf16 v[16:31], v[178:181], v[80:83], v[16:31]
	v_add_u32_e32 v169, s12, v198
	ds_read_b128 v[178:181], v169
	v_cvt_pk_bf16_f32 v89, v90, v91
	v_cvt_pk_bf16_f32 v90, v92, v93
	v_cvt_pk_bf16_f32 v91, v94, v95
	s_waitcnt lgkmcnt(5)
	v_mfma_f32_32x32x16_bf16 v[0:15], v[206:209], v[80:83], v[0:15]
	ds_read_b128 v[206:209], v169 offset:32
	v_mfma_f32_16x16x32_bf16 v[248:251], v[226:229], v[88:91], v[248:251]
	s_add_i32 s10, s10, 64
	s_add_i32 s11, s11, 1
	s_waitcnt lgkmcnt(5)
	v_mfma_f32_32x32x16_bf16 v[48:63], v[210:213], v[88:91], v[48:63]
	ds_read_b128 v[210:213], v169 offset:64
	v_lshl_add_u64 v[170:171], v[170:171], 0, s[72:73]
	s_waitcnt lgkmcnt(5)
	v_mfma_f32_32x32x16_bf16 v[32:47], v[214:217], v[88:91], v[32:47]
	ds_read_b128 v[214:217], v169 offset:96
	v_lshl_add_u64 v[172:173], v[172:173], 0, s[72:73]
	s_waitcnt lgkmcnt(5)
	v_mfma_f32_32x32x16_bf16 v[16:31], v[230:233], v[88:91], v[16:31]
	ds_read_b128 v[230:233], v169 offset:4608
	v_lshl_add_u64 v[174:175], v[174:175], 0, s[0:1]
	s_mov_b32 s13, s12
	s_waitcnt lgkmcnt(5)
	v_mfma_f32_32x32x16_bf16 v[0:15], v[236:239], v[88:91], v[0:15]
	ds_read_b128 v[236:239], v169 offset:4640
	s_add_i32 s12, s13, 0x8c00
	s_cmp_lg_u32 s13, 0x11800
	s_cselect_b32 s12, s12, 0
	s_cmp_gt_i32 s24, -1
	s_cselect_b64 vcc, -1, 0
	s_nop 1
	v_cndmask_b32_e32 v80, v204, v205, vcc
	v_mov_b32_e32 v81, v80
	v_mov_b32_e32 v82, v80
	v_mov_b32_e32 v83, v80
	v_mov_b32_e32 v84, v80
	v_mov_b32_e32 v85, v80
	v_mov_b32_e32 v86, v80
	v_mov_b32_e32 v87, v80
	v_mov_b32_e32 v88, v80
	v_mov_b32_e32 v89, v80
	v_mov_b32_e32 v90, v80
	v_mov_b32_e32 v91, v80
	v_mov_b32_e32 v92, v80
	v_mov_b32_e32 v93, v80
	v_mov_b32_e32 v94, v80
	v_mov_b32_e32 v95, v80
	s_nop 0
	s_branch .Lfar_p2_main
.Lfar_p2_tailnp:
	v_mfma_f32_16x16x32_bf16 v[248:251], v[226:229], v[80:83], v[248:251]
	v_exp_f32_e32 v88, v88
	v_exp_f32_e32 v89, v89
	v_exp_f32_e32 v90, v90
	v_mfma_f32_32x32x16_bf16 v[48:63], v[230:233], v[80:83], v[48:63]
	ds_read_b128 v[230:233], v169 offset:26720
	v_exp_f32_e32 v91, v91
	v_exp_f32_e32 v92, v92
	v_exp_f32_e32 v93, v93
	s_waitcnt lgkmcnt(5)
	v_mfma_f32_32x32x16_bf16 v[32:47], v[236:239], v[80:83], v[32:47]
	ds_read_b128 v[236:239], v169 offset:31328
	s_cmpk_gt_u32 s11, 0x7d
	s_cbranch_scc1 .Lfar_p2_noloadb
	global_load_dwordx4 v[128:131], v[174:175], off
	global_load_dwordx4 v[132:135], v[172:173], off
	global_load_dwordx4 v[136:139], v[170:171], off
.Lfar_p2_noloadb:
	v_exp_f32_e32 v94, v94
	v_exp_f32_e32 v95, v95
	v_cvt_pk_bf16_f32 v88, v88, v89
	s_waitcnt lgkmcnt(5)
	v_mfma_f32_32x32x16_bf16 v[16:31], v[178:181], v[80:83], v[16:31]
	v_cvt_pk_bf16_f32 v89, v90, v91
	v_cvt_pk_bf16_f32 v90, v92, v93
	v_cvt_pk_bf16_f32 v91, v94, v95
	s_waitcnt lgkmcnt(4)
	v_mfma_f32_32x32x16_bf16 v[0:15], v[206:209], v[80:83], v[0:15]
	v_mfma_f32_16x16x32_bf16 v[248:251], v[226:229], v[88:91], v[248:251]
	s_add_i32 s10, s10, 64
	s_add_i32 s11, s11, 1
	s_waitcnt lgkmcnt(3)
	v_mfma_f32_32x32x16_bf16 v[48:63], v[210:213], v[88:91], v[48:63]
	v_lshl_add_u64 v[170:171], v[170:171], 0, s[72:73]
	s_waitcnt lgkmcnt(2)
	v_mfma_f32_32x32x16_bf16 v[32:47], v[214:217], v[88:91], v[32:47]
	v_lshl_add_u64 v[172:173], v[172:173], 0, s[72:73]
	s_waitcnt lgkmcnt(1)
	v_mfma_f32_32x32x16_bf16 v[16:31], v[230:233], v[88:91], v[16:31]
	v_lshl_add_u64 v[174:175], v[174:175], 0, s[0:1]
	s_mov_b32 s13, s12
	s_waitcnt lgkmcnt(0)
	v_mfma_f32_32x32x16_bf16 v[0:15], v[236:239], v[88:91], v[0:15]
	s_cmpk_lg_i32 s10, 0x2000
	s_cbranch_scc0 .LBB0_1019
	s_branch .LBB0_1060

.LBB0_1133:
	s_and_b64 s[28:29], s[4:5], exec
	s_cbranch_scc1 .Lscan_B
	s_add_i32 s23, s21, 0
	s_min_u32 s23, s23, 63
	s_sub_i32 s24, 63, s23
	v_mov_b32_e32 v8, s24
	v_mov_b32_e32 v9, s23
	v_cndmask_b32_e64 v8, v8, v9, s[2:3]
	v_or_b32_e32 v28, v8, v31
	v_mov_b32_e32 v106, v28
	v_lshlrev_b32_e32 v8, 1, v28
	v_ashrrev_i32_e32 v9, 31, v8
	v_lshl_add_u64 v[8:9], v[8:9], 2, s[12:13]
	v_ashrrev_i32_e32 v29, 31, v28
	global_load_dwordx2 v[98:99], v[8:9], off
	v_lshlrev_b64 v[8:9], 15, v[28:29]
	v_lshl_add_u64 v[104:105], v[12:13], 0, v[8:9]
	global_load_dwordx4 v[100:103], v[104:105], off
	s_add_i32 s23, s21, 1
	s_min_u32 s23, s23, 63
	s_sub_i32 s24, 63, s23
	v_mov_b32_e32 v8, s24
	v_mov_b32_e32 v9, s23
	v_cndmask_b32_e64 v8, v8, v9, s[2:3]
	v_or_b32_e32 v28, v8, v31
	v_mov_b32_e32 v116, v28
	v_lshlrev_b32_e32 v8, 1, v28
	v_ashrrev_i32_e32 v9, 31, v8
	v_lshl_add_u64 v[8:9], v[8:9], 2, s[12:13]
	v_ashrrev_i32_e32 v29, 31, v28
	global_load_dwordx2 v[108:109], v[8:9], off
	v_lshlrev_b64 v[8:9], 15, v[28:29]
	v_lshl_add_u64 v[114:115], v[12:13], 0, v[8:9]
	global_load_dwordx4 v[110:113], v[114:115], off
	s_add_i32 s23, s21, 2
	s_min_u32 s23, s23, 63
	s_sub_i32 s24, 63, s23
	v_mov_b32_e32 v8, s24
	v_mov_b32_e32 v9, s23
	v_cndmask_b32_e64 v8, v8, v9, s[2:3]
	v_or_b32_e32 v28, v8, v31
	v_mov_b32_e32 v142, v28
	v_lshlrev_b32_e32 v8, 1, v28
	v_ashrrev_i32_e32 v9, 31, v8
	v_lshl_add_u64 v[8:9], v[8:9], 2, s[12:13]
	v_ashrrev_i32_e32 v29, 31, v28
	global_load_dwordx2 v[134:135], v[8:9], off
	v_lshlrev_b64 v[8:9], 15, v[28:29]
	v_lshl_add_u64 v[140:141], v[12:13], 0, v[8:9]
	global_load_dwordx4 v[136:139], v[140:141], off
	s_add_i32 s23, s21, 3
	s_min_u32 s23, s23, 63
	s_sub_i32 s24, 63, s23
	v_mov_b32_e32 v8, s24
	v_mov_b32_e32 v9, s23
	v_cndmask_b32_e64 v8, v8, v9, s[2:3]
	v_or_b32_e32 v28, v8, v31
	v_mov_b32_e32 v152, v28
	v_lshlrev_b32_e32 v8, 1, v28
	v_ashrrev_i32_e32 v9, 31, v8
	v_lshl_add_u64 v[8:9], v[8:9], 2, s[12:13]
	v_ashrrev_i32_e32 v29, 31, v28
	global_load_dwordx2 v[144:145], v[8:9], off
	v_lshlrev_b64 v[8:9], 15, v[28:29]
	v_lshl_add_u64 v[150:151], v[12:13], 0, v[8:9]
	global_load_dwordx4 v[146:149], v[150:151], off
	s_waitcnt vmcnt(6)
	v_cvt_pk_bf16_f32 v34, v18, v19
	v_cvt_pk_bf16_f32 v35, v20, v21
	v_cvt_pk_bf16_f32 v36, v22, v23
	v_cvt_pk_bf16_f32 v37, v16, v17
	global_store_dwordx4 v[104:105], v[34:37], off
	v_add_f32_e32 v24, v32, v98
	v_max_f32_e32 v26, v99, v99
	v_max_f32_e32 v32, v24, v26
	v_sub_f32_e32 v24, v24, v32
	v_sub_f32_e32 v25, v99, v32
	v_mul_f32_e32 v24, 0x3fb8aa3b, v24
	v_mul_f32_e32 v25, 0x3fb8aa3b, v25
	v_exp_f32_e32 v24, v24
	v_exp_f32_e32 v26, v25
	s_nop 0
	v_mov_b32_e32 v25, v24
	v_mov_b32_e32 v27, v26
	v_lshlrev_b32_e32 v28, 16, v100
	v_and_b32_e32 v29, 0xffff0000, v100
	v_lshlrev_b32_e32 v8, 16, v101
	v_and_b32_e32 v9, 0xffff0000, v101
	v_pk_mul_f32 v[8:9], v[26:27], v[8:9]
	v_pk_mul_f32 v[28:29], v[26:27], v[28:29]
	v_pk_fma_f32 v[20:21], v[20:21], v[24:25], v[8:9]
	v_lshlrev_b32_e32 v8, 16, v102
	v_and_b32_e32 v9, 0xffff0000, v102
	v_pk_mul_f32 v[8:9], v[26:27], v[8:9]
	s_nop 0
	v_pk_fma_f32 v[22:23], v[22:23], v[24:25], v[8:9]
	v_lshlrev_b32_e32 v8, 16, v103
	v_and_b32_e32 v9, 0xffff0000, v103
	v_pk_mul_f32 v[8:9], v[26:27], v[8:9]
	v_pk_fma_f32 v[18:19], v[18:19], v[24:25], v[28:29]
	s_nop 0
	v_pk_fma_f32 v[16:17], v[16:17], v[24:25], v[8:9]
	s_add_i32 s23, s21, 4
	s_min_u32 s23, s23, 63
	s_sub_i32 s24, 63, s23
	v_mov_b32_e32 v8, s24
	v_mov_b32_e32 v9, s23
	v_cndmask_b32_e64 v8, v8, v9, s[2:3]
	v_or_b32_e32 v28, v8, v31
	v_mov_b32_e32 v106, v28
	v_lshlrev_b32_e32 v8, 1, v28
	v_ashrrev_i32_e32 v9, 31, v8
	v_lshl_add_u64 v[8:9], v[8:9], 2, s[12:13]
	v_ashrrev_i32_e32 v29, 31, v28
	global_load_dwordx2 v[98:99], v[8:9], off
	v_lshlrev_b64 v[8:9], 15, v[28:29]
	v_lshl_add_u64 v[104:105], v[12:13], 0, v[8:9]
	global_load_dwordx4 v[100:103], v[104:105], off
	s_waitcnt vmcnt(7)
	v_cvt_pk_bf16_f32 v34, v18, v19
	v_cvt_pk_bf16_f32 v35, v20, v21
	v_cvt_pk_bf16_f32 v36, v22, v23
	v_cvt_pk_bf16_f32 v37, v16, v17
	global_store_dwordx4 v[114:115], v[34:37], off
	v_add_f32_e32 v24, v32, v108
	v_max_f32_e32 v26, v109, v109
	v_max_f32_e32 v32, v24, v26
	v_sub_f32_e32 v24, v24, v32
	v_sub_f32_e32 v25, v109, v32
	v_mul_f32_e32 v24, 0x3fb8aa3b, v24
	v_mul_f32_e32 v25, 0x3fb8aa3b, v25
	v_exp_f32_e32 v24, v24
	v_exp_f32_e32 v26, v25
	s_nop 0
	v_mov_b32_e32 v25, v24
	v_mov_b32_e32 v27, v26
	v_lshlrev_b32_e32 v28, 16, v110
	v_and_b32_e32 v29, 0xffff0000, v110
	v_lshlrev_b32_e32 v8, 16, v111
	v_and_b32_e32 v9, 0xffff0000, v111
	v_pk_mul_f32 v[8:9], v[26:27], v[8:9]
	v_pk_mul_f32 v[28:29], v[26:27], v[28:29]
	v_pk_fma_f32 v[20:21], v[20:21], v[24:25], v[8:9]
	v_lshlrev_b32_e32 v8, 16, v112
	v_and_b32_e32 v9, 0xffff0000, v112
	v_pk_mul_f32 v[8:9], v[26:27], v[8:9]
	s_nop 0
	v_pk_fma_f32 v[22:23], v[22:23], v[24:25], v[8:9]
	v_lshlrev_b32_e32 v8, 16, v113
	v_and_b32_e32 v9, 0xffff0000, v113
	v_pk_mul_f32 v[8:9], v[26:27], v[8:9]
	v_pk_fma_f32 v[18:19], v[18:19], v[24:25], v[28:29]
	s_nop 0
	v_pk_fma_f32 v[16:17], v[16:17], v[24:25], v[8:9]
	s_add_i32 s23, s21, 5
	s_min_u32 s23, s23, 63
	s_sub_i32 s24, 63, s23
	v_mov_b32_e32 v8, s24
	v_mov_b32_e32 v9, s23
	v_cndmask_b32_e64 v8, v8, v9, s[2:3]
	v_or_b32_e32 v28, v8, v31
	v_mov_b32_e32 v116, v28
	v_lshlrev_b32_e32 v8, 1, v28
	v_ashrrev_i32_e32 v9, 31, v8
	v_lshl_add_u64 v[8:9], v[8:9], 2, s[12:13]
	v_ashrrev_i32_e32 v29, 31, v28
	global_load_dwordx2 v[108:109], v[8:9], off
	v_lshlrev_b64 v[8:9], 15, v[28:29]
	v_lshl_add_u64 v[114:115], v[12:13], 0, v[8:9]
	global_load_dwordx4 v[110:113], v[114:115], off
	s_waitcnt vmcnt(8)
	v_cvt_pk_bf16_f32 v34, v18, v19
	v_cvt_pk_bf16_f32 v35, v20, v21
	v_cvt_pk_bf16_f32 v36, v22, v23
	v_cvt_pk_bf16_f32 v37, v16, v17
	global_store_dwordx4 v[140:141], v[34:37], off
	v_add_f32_e32 v24, v32, v134
	v_max_f32_e32 v26, v135, v135
	v_max_f32_e32 v32, v24, v26
	v_sub_f32_e32 v24, v24, v32
	v_sub_f32_e32 v25, v135, v32
	v_mul_f32_e32 v24, 0x3fb8aa3b, v24
	v_mul_f32_e32 v25, 0x3fb8aa3b, v25
	v_exp_f32_e32 v24, v24
	v_exp_f32_e32 v26, v25
	s_nop 0
	v_mov_b32_e32 v25, v24
	v_mov_b32_e32 v27, v26
	v_lshlrev_b32_e32 v28, 16, v136
	v_and_b32_e32 v29, 0xffff0000, v136
	v_lshlrev_b32_e32 v8, 16, v137
	v_and_b32_e32 v9, 0xffff0000, v137
	v_pk_mul_f32 v[8:9], v[26:27], v[8:9]
	v_pk_mul_f32 v[28:29], v[26:27], v[28:29]
	v_pk_fma_f32 v[20:21], v[20:21], v[24:25], v[8:9]
	v_lshlrev_b32_e32 v8, 16, v138
	v_and_b32_e32 v9, 0xffff0000, v138
	v_pk_mul_f32 v[8:9], v[26:27], v[8:9]
	s_nop 0
	v_pk_fma_f32 v[22:23], v[22:23], v[24:25], v[8:9]
	v_lshlrev_b32_e32 v8, 16, v139
	v_and_b32_e32 v9, 0xffff0000, v139
	v_pk_mul_f32 v[8:9], v[26:27], v[8:9]
	v_pk_fma_f32 v[18:19], v[18:19], v[24:25], v[28:29]
	s_nop 0
	v_pk_fma_f32 v[16:17], v[16:17], v[24:25], v[8:9]
	s_add_i32 s23, s21, 6
	s_min_u32 s23, s23, 63
	s_sub_i32 s24, 63, s23
	v_mov_b32_e32 v8, s24
	v_mov_b32_e32 v9, s23
	v_cndmask_b32_e64 v8, v8, v9, s[2:3]
	v_or_b32_e32 v28, v8, v31
	v_mov_b32_e32 v142, v28
	v_lshlrev_b32_e32 v8, 1, v28
	v_ashrrev_i32_e32 v9, 31, v8
	v_lshl_add_u64 v[8:9], v[8:9], 2, s[12:13]
	v_ashrrev_i32_e32 v29, 31, v28
	global_load_dwordx2 v[134:135], v[8:9], off
	v_lshlrev_b64 v[8:9], 15, v[28:29]
	v_lshl_add_u64 v[140:141], v[12:13], 0, v[8:9]
	global_load_dwordx4 v[136:139], v[140:141], off
	s_waitcnt vmcnt(9)
	v_cvt_pk_bf16_f32 v34, v18, v19
	v_cvt_pk_bf16_f32 v35, v20, v21
	v_cvt_pk_bf16_f32 v36, v22, v23
	v_cvt_pk_bf16_f32 v37, v16, v17
	global_store_dwordx4 v[150:151], v[34:37], off
	v_add_f32_e32 v24, v32, v144
	v_max_f32_e32 v26, v145, v145
	v_max_f32_e32 v32, v24, v26
	v_sub_f32_e32 v24, v24, v32
	v_sub_f32_e32 v25, v145, v32
	v_mul_f32_e32 v24, 0x3fb8aa3b, v24
	v_mul_f32_e32 v25, 0x3fb8aa3b, v25
	v_exp_f32_e32 v24, v24
	v_exp_f32_e32 v26, v25
	s_nop 0
	v_mov_b32_e32 v25, v24
	v_mov_b32_e32 v27, v26
	v_lshlrev_b32_e32 v28, 16, v146
	v_and_b32_e32 v29, 0xffff0000, v146
	v_lshlrev_b32_e32 v8, 16, v147
	v_and_b32_e32 v9, 0xffff0000, v147
	v_pk_mul_f32 v[8:9], v[26:27], v[8:9]
	v_pk_mul_f32 v[28:29], v[26:27], v[28:29]
	v_pk_fma_f32 v[20:21], v[20:21], v[24:25], v[8:9]
	v_lshlrev_b32_e32 v8, 16, v148
	v_and_b32_e32 v9, 0xffff0000, v148
	v_pk_mul_f32 v[8:9], v[26:27], v[8:9]
	s_nop 0
	v_pk_fma_f32 v[22:23], v[22:23], v[24:25], v[8:9]
	v_lshlrev_b32_e32 v8, 16, v149
	v_and_b32_e32 v9, 0xffff0000, v149
	v_pk_mul_f32 v[8:9], v[26:27], v[8:9]
	v_pk_fma_f32 v[18:19], v[18:19], v[24:25], v[28:29]
	s_nop 0
	v_pk_fma_f32 v[16:17], v[16:17], v[24:25], v[8:9]
	s_add_i32 s23, s21, 7
	s_min_u32 s23, s23, 63
	s_sub_i32 s24, 63, s23
	v_mov_b32_e32 v8, s24
	v_mov_b32_e32 v9, s23
	v_cndmask_b32_e64 v8, v8, v9, s[2:3]
	v_or_b32_e32 v28, v8, v31
	v_mov_b32_e32 v152, v28
	v_lshlrev_b32_e32 v8, 1, v28
	v_ashrrev_i32_e32 v9, 31, v8
	v_lshl_add_u64 v[8:9], v[8:9], 2, s[12:13]
	v_ashrrev_i32_e32 v29, 31, v28
	global_load_dwordx2 v[144:145], v[8:9], off
	v_lshlrev_b64 v[8:9], 15, v[28:29]
	v_lshl_add_u64 v[150:151], v[12:13], 0, v[8:9]
	global_load_dwordx4 v[146:149], v[150:151], off
	s_mov_b32 s21, 4
.Lscan_A_loop:
	s_waitcnt vmcnt(9)
	v_cvt_pk_bf16_f32 v34, v18, v19
	v_cvt_pk_bf16_f32 v35, v20, v21
	v_cvt_pk_bf16_f32 v36, v22, v23
	v_cvt_pk_bf16_f32 v37, v16, v17
	global_store_dwordx4 v[104:105], v[34:37], off
	v_add_f32_e32 v24, v32, v98
	v_max_f32_e32 v26, v99, v99
	v_max_f32_e32 v32, v24, v26
	v_sub_f32_e32 v24, v24, v32
	v_sub_f32_e32 v25, v99, v32
	v_mul_f32_e32 v24, 0x3fb8aa3b, v24
	v_mul_f32_e32 v25, 0x3fb8aa3b, v25
	v_exp_f32_e32 v24, v24
	v_exp_f32_e32 v26, v25
	s_nop 0
	v_mov_b32_e32 v25, v24
	v_mov_b32_e32 v27, v26
	v_lshlrev_b32_e32 v28, 16, v100
	v_and_b32_e32 v29, 0xffff0000, v100
	v_lshlrev_b32_e32 v8, 16, v101
	v_and_b32_e32 v9, 0xffff0000, v101
	v_pk_mul_f32 v[8:9], v[26:27], v[8:9]
	v_pk_mul_f32 v[28:29], v[26:27], v[28:29]
	v_pk_fma_f32 v[20:21], v[20:21], v[24:25], v[8:9]
	v_lshlrev_b32_e32 v8, 16, v102
	v_and_b32_e32 v9, 0xffff0000, v102
	v_pk_mul_f32 v[8:9], v[26:27], v[8:9]
	s_nop 0
	v_pk_fma_f32 v[22:23], v[22:23], v[24:25], v[8:9]
	v_lshlrev_b32_e32 v8, 16, v103
	v_and_b32_e32 v9, 0xffff0000, v103
	v_pk_mul_f32 v[8:9], v[26:27], v[8:9]
	v_pk_fma_f32 v[18:19], v[18:19], v[24:25], v[28:29]
	s_nop 0
	v_pk_fma_f32 v[16:17], v[16:17], v[24:25], v[8:9]
	s_add_i32 s23, s21, 4
	s_min_u32 s23, s23, 63
	s_sub_i32 s24, 63, s23
	v_mov_b32_e32 v8, s24
	v_mov_b32_e32 v9, s23
	v_cndmask_b32_e64 v8, v8, v9, s[2:3]
	v_or_b32_e32 v28, v8, v31
	v_mov_b32_e32 v106, v28
	v_lshlrev_b32_e32 v8, 1, v28
	v_ashrrev_i32_e32 v9, 31, v8
	v_lshl_add_u64 v[8:9], v[8:9], 2, s[12:13]
	v_ashrrev_i32_e32 v29, 31, v28
	global_load_dwordx2 v[98:99], v[8:9], off
	v_lshlrev_b64 v[8:9], 15, v[28:29]
	v_lshl_add_u64 v[104:105], v[12:13], 0, v[8:9]
	global_load_dwordx4 v[100:103], v[104:105], off
	s_waitcnt vmcnt(9)
	v_cvt_pk_bf16_f32 v34, v18, v19
	v_cvt_pk_bf16_f32 v35, v20, v21
	v_cvt_pk_bf16_f32 v36, v22, v23
	v_cvt_pk_bf16_f32 v37, v16, v17
	global_store_dwordx4 v[114:115], v[34:37], off
	v_add_f32_e32 v24, v32, v108
	v_max_f32_e32 v26, v109, v109
	v_max_f32_e32 v32, v24, v26
	v_sub_f32_e32 v24, v24, v32
	v_sub_f32_e32 v25, v109, v32
	v_mul_f32_e32 v24, 0x3fb8aa3b, v24
	v_mul_f32_e32 v25, 0x3fb8aa3b, v25
	v_exp_f32_e32 v24, v24
	v_exp_f32_e32 v26, v25
	s_nop 0
	v_mov_b32_e32 v25, v24
	v_mov_b32_e32 v27, v26
	v_lshlrev_b32_e32 v28, 16, v110
	v_and_b32_e32 v29, 0xffff0000, v110
	v_lshlrev_b32_e32 v8, 16, v111
	v_and_b32_e32 v9, 0xffff0000, v111
	v_pk_mul_f32 v[8:9], v[26:27], v[8:9]
	v_pk_mul_f32 v[28:29], v[26:27], v[28:29]
	v_pk_fma_f32 v[20:21], v[20:21], v[24:25], v[8:9]
	v_lshlrev_b32_e32 v8, 16, v112
	v_and_b32_e32 v9, 0xffff0000, v112
	v_pk_mul_f32 v[8:9], v[26:27], v[8:9]
	s_nop 0
	v_pk_fma_f32 v[22:23], v[22:23], v[24:25], v[8:9]
	v_lshlrev_b32_e32 v8, 16, v113
	v_and_b32_e32 v9, 0xffff0000, v113
	v_pk_mul_f32 v[8:9], v[26:27], v[8:9]
	v_pk_fma_f32 v[18:19], v[18:19], v[24:25], v[28:29]
	s_nop 0
	v_pk_fma_f32 v[16:17], v[16:17], v[24:25], v[8:9]
	s_add_i32 s23, s21, 5
	s_min_u32 s23, s23, 63
	s_sub_i32 s24, 63, s23
	v_mov_b32_e32 v8, s24
	v_mov_b32_e32 v9, s23
	v_cndmask_b32_e64 v8, v8, v9, s[2:3]
	v_or_b32_e32 v28, v8, v31
	v_mov_b32_e32 v116, v28
	v_lshlrev_b32_e32 v8, 1, v28
	v_ashrrev_i32_e32 v9, 31, v8
	v_lshl_add_u64 v[8:9], v[8:9], 2, s[12:13]
	v_ashrrev_i32_e32 v29, 31, v28
	global_load_dwordx2 v[108:109], v[8:9], off
	v_lshlrev_b64 v[8:9], 15, v[28:29]
	v_lshl_add_u64 v[114:115], v[12:13], 0, v[8:9]
	global_load_dwordx4 v[110:113], v[114:115], off
	s_waitcnt vmcnt(9)
	v_cvt_pk_bf16_f32 v34, v18, v19
	v_cvt_pk_bf16_f32 v35, v20, v21
	v_cvt_pk_bf16_f32 v36, v22, v23
	v_cvt_pk_bf16_f32 v37, v16, v17
	global_store_dwordx4 v[140:141], v[34:37], off
	v_add_f32_e32 v24, v32, v134
	v_max_f32_e32 v26, v135, v135
	v_max_f32_e32 v32, v24, v26
	v_sub_f32_e32 v24, v24, v32
	v_sub_f32_e32 v25, v135, v32
	v_mul_f32_e32 v24, 0x3fb8aa3b, v24
	v_mul_f32_e32 v25, 0x3fb8aa3b, v25
	v_exp_f32_e32 v24, v24
	v_exp_f32_e32 v26, v25
	s_nop 0
	v_mov_b32_e32 v25, v24
	v_mov_b32_e32 v27, v26
	v_lshlrev_b32_e32 v28, 16, v136
	v_and_b32_e32 v29, 0xffff0000, v136
	v_lshlrev_b32_e32 v8, 16, v137
	v_and_b32_e32 v9, 0xffff0000, v137
	v_pk_mul_f32 v[8:9], v[26:27], v[8:9]
	v_pk_mul_f32 v[28:29], v[26:27], v[28:29]
	v_pk_fma_f32 v[20:21], v[20:21], v[24:25], v[8:9]
	v_lshlrev_b32_e32 v8, 16, v138
	v_and_b32_e32 v9, 0xffff0000, v138
	v_pk_mul_f32 v[8:9], v[26:27], v[8:9]
	s_nop 0
	v_pk_fma_f32 v[22:23], v[22:23], v[24:25], v[8:9]
	v_lshlrev_b32_e32 v8, 16, v139
	v_and_b32_e32 v9, 0xffff0000, v139
	v_pk_mul_f32 v[8:9], v[26:27], v[8:9]
	v_pk_fma_f32 v[18:19], v[18:19], v[24:25], v[28:29]
	s_nop 0
	v_pk_fma_f32 v[16:17], v[16:17], v[24:25], v[8:9]
	s_add_i32 s23, s21, 6
	s_min_u32 s23, s23, 63
	s_sub_i32 s24, 63, s23
	v_mov_b32_e32 v8, s24
	v_mov_b32_e32 v9, s23
	v_cndmask_b32_e64 v8, v8, v9, s[2:3]
	v_or_b32_e32 v28, v8, v31
	v_mov_b32_e32 v142, v28
	v_lshlrev_b32_e32 v8, 1, v28
	v_ashrrev_i32_e32 v9, 31, v8
	v_lshl_add_u64 v[8:9], v[8:9], 2, s[12:13]
	v_ashrrev_i32_e32 v29, 31, v28
	global_load_dwordx2 v[134:135], v[8:9], off
	v_lshlrev_b64 v[8:9], 15, v[28:29]
	v_lshl_add_u64 v[140:141], v[12:13], 0, v[8:9]
	global_load_dwordx4 v[136:139], v[140:141], off
	s_waitcnt vmcnt(9)
	v_cvt_pk_bf16_f32 v34, v18, v19
	v_cvt_pk_bf16_f32 v35, v20, v21
	v_cvt_pk_bf16_f32 v36, v22, v23
	v_cvt_pk_bf16_f32 v37, v16, v17
	global_store_dwordx4 v[150:151], v[34:37], off
	v_add_f32_e32 v24, v32, v144
	v_max_f32_e32 v26, v145, v145
	v_max_f32_e32 v32, v24, v26
	v_sub_f32_e32 v24, v24, v32
	v_sub_f32_e32 v25, v145, v32
	v_mul_f32_e32 v24, 0x3fb8aa3b, v24
	v_mul_f32_e32 v25, 0x3fb8aa3b, v25
	v_exp_f32_e32 v24, v24
	v_exp_f32_e32 v26, v25
	s_nop 0
	v_mov_b32_e32 v25, v24
	v_mov_b32_e32 v27, v26
	v_lshlrev_b32_e32 v28, 16, v146
	v_and_b32_e32 v29, 0xffff0000, v146
	v_lshlrev_b32_e32 v8, 16, v147
	v_and_b32_e32 v9, 0xffff0000, v147
	v_pk_mul_f32 v[8:9], v[26:27], v[8:9]
	v_pk_mul_f32 v[28:29], v[26:27], v[28:29]
	v_pk_fma_f32 v[20:21], v[20:21], v[24:25], v[8:9]
	v_lshlrev_b32_e32 v8, 16, v148
	v_and_b32_e32 v9, 0xffff0000, v148
	v_pk_mul_f32 v[8:9], v[26:27], v[8:9]
	s_nop 0
	v_pk_fma_f32 v[22:23], v[22:23], v[24:25], v[8:9]
	v_lshlrev_b32_e32 v8, 16, v149
	v_and_b32_e32 v9, 0xffff0000, v149
	v_pk_mul_f32 v[8:9], v[26:27], v[8:9]
	v_pk_fma_f32 v[18:19], v[18:19], v[24:25], v[28:29]
	s_nop 0
	v_pk_fma_f32 v[16:17], v[16:17], v[24:25], v[8:9]
	s_add_i32 s23, s21, 7
	s_min_u32 s23, s23, 63
	s_sub_i32 s24, 63, s23
	v_mov_b32_e32 v8, s24
	v_mov_b32_e32 v9, s23
	v_cndmask_b32_e64 v8, v8, v9, s[2:3]
	v_or_b32_e32 v28, v8, v31
	v_mov_b32_e32 v152, v28
	v_lshlrev_b32_e32 v8, 1, v28
	v_ashrrev_i32_e32 v9, 31, v8
	v_lshl_add_u64 v[8:9], v[8:9], 2, s[12:13]
	v_ashrrev_i32_e32 v29, 31, v28
	global_load_dwordx2 v[144:145], v[8:9], off
	v_lshlrev_b64 v[8:9], 15, v[28:29]
	v_lshl_add_u64 v[150:151], v[12:13], 0, v[8:9]
	global_load_dwordx4 v[146:149], v[150:151], off
	s_add_i32 s21, s21, 4
	s_cmp_lt_u32 s21, 64
	s_cbranch_scc1 .Lscan_A_loop
	s_branch .LBB0_1130
.Lscan_B:
	s_add_i32 s23, s21, 0
	s_min_u32 s23, s23, 63
	s_sub_i32 s24, 63, s23
	v_mov_b32_e32 v8, s24
	v_mov_b32_e32 v9, s23
	v_cndmask_b32_e64 v8, v8, v9, s[2:3]
	v_or_b32_e32 v28, v8, v31
	v_mov_b32_e32 v106, v28
	v_lshlrev_b32_e32 v8, 1, v28
	v_ashrrev_i32_e32 v9, 31, v8
	v_lshl_add_u64 v[8:9], v[8:9], 2, s[12:13]
	v_ashrrev_i32_e32 v29, 31, v28
	global_load_dwordx2 v[98:99], v[8:9], off
	v_lshlrev_b64 v[8:9], 15, v[28:29]
	v_lshl_add_u64 v[104:105], v[12:13], 0, v[8:9]
	global_load_dwordx4 v[100:103], v[104:105], off
	v_lshlrev_b64 v[8:9], 9, v[28:29]
	v_lshl_add_u64 v[162:163], v[14:15], 0, v[8:9]
	s_and_saveexec_b64 s[18:19], vcc
	global_load_dwordx4 v[154:157], v[162:163], off offset:16
	global_load_dwordx4 v[158:161], v[162:163], off
	s_or_b64 exec, exec, s[18:19]
	s_add_i32 s23, s21, 1
	s_min_u32 s23, s23, 63
	s_sub_i32 s24, 63, s23
	v_mov_b32_e32 v8, s24
	v_mov_b32_e32 v9, s23
	v_cndmask_b32_e64 v8, v8, v9, s[2:3]
	v_or_b32_e32 v28, v8, v31
	v_mov_b32_e32 v116, v28
	v_lshlrev_b32_e32 v8, 1, v28
	v_ashrrev_i32_e32 v9, 31, v8
	v_lshl_add_u64 v[8:9], v[8:9], 2, s[12:13]
	v_ashrrev_i32_e32 v29, 31, v28
	global_load_dwordx2 v[108:109], v[8:9], off
	v_lshlrev_b64 v[8:9], 15, v[28:29]
	v_lshl_add_u64 v[114:115], v[12:13], 0, v[8:9]
	global_load_dwordx4 v[110:113], v[114:115], off
	v_lshlrev_b64 v[8:9], 9, v[28:29]
	v_lshl_add_u64 v[172:173], v[14:15], 0, v[8:9]
	s_and_saveexec_b64 s[18:19], vcc
	global_load_dwordx4 v[164:167], v[172:173], off offset:16
	global_load_dwordx4 v[168:171], v[172:173], off
	s_or_b64 exec, exec, s[18:19]
	s_add_i32 s23, s21, 2
	s_min_u32 s23, s23, 63
	s_sub_i32 s24, 63, s23
	v_mov_b32_e32 v8, s24
	v_mov_b32_e32 v9, s23
	v_cndmask_b32_e64 v8, v8, v9, s[2:3]
	v_or_b32_e32 v28, v8, v31
	v_mov_b32_e32 v142, v28
	v_lshlrev_b32_e32 v8, 1, v28
	v_ashrrev_i32_e32 v9, 31, v8
	v_lshl_add_u64 v[8:9], v[8:9], 2, s[12:13]
	v_ashrrev_i32_e32 v29, 31, v28
	global_load_dwordx2 v[134:135], v[8:9], off
	v_lshlrev_b64 v[8:9], 15, v[28:29]
	v_lshl_add_u64 v[140:141], v[12:13], 0, v[8:9]
	global_load_dwordx4 v[136:139], v[140:141], off
	v_lshlrev_b64 v[8:9], 9, v[28:29]
	v_lshl_add_u64 v[186:187], v[14:15], 0, v[8:9]
	s_and_saveexec_b64 s[18:19], vcc
	global_load_dwordx4 v[178:181], v[186:187], off offset:16
	global_load_dwordx4 v[182:185], v[186:187], off
	s_or_b64 exec, exec, s[18:19]
	s_add_i32 s23, s21, 3
	s_min_u32 s23, s23, 63
	s_sub_i32 s24, 63, s23
	v_mov_b32_e32 v8, s24
	v_mov_b32_e32 v9, s23
	v_cndmask_b32_e64 v8, v8, v9, s[2:3]
	v_or_b32_e32 v28, v8, v31
	v_mov_b32_e32 v152, v28
	v_lshlrev_b32_e32 v8, 1, v28
	v_ashrrev_i32_e32 v9, 31, v8
	v_lshl_add_u64 v[8:9], v[8:9], 2, s[12:13]
	v_ashrrev_i32_e32 v29, 31, v28
	global_load_dwordx2 v[144:145], v[8:9], off
	v_lshlrev_b64 v[8:9], 15, v[28:29]
	v_lshl_add_u64 v[150:151], v[12:13], 0, v[8:9]
	global_load_dwordx4 v[146:149], v[150:151], off
	v_lshlrev_b64 v[8:9], 9, v[28:29]
	v_lshl_add_u64 v[196:197], v[14:15], 0, v[8:9]
	s_and_saveexec_b64 s[18:19], vcc
	global_load_dwordx4 v[188:191], v[196:197], off offset:16
	global_load_dwordx4 v[192:195], v[196:197], off
	s_or_b64 exec, exec, s[18:19]
	s_waitcnt vmcnt(12)
	v_cvt_pk_bf16_f32 v34, v18, v19
	v_cvt_pk_bf16_f32 v35, v20, v21
	v_cvt_pk_bf16_f32 v36, v22, v23
	v_cvt_pk_bf16_f32 v37, v16, v17
	global_store_dwordx4 v[104:105], v[34:37], off
	v_mov_b32_e32 v28, v106
	v_ashrrev_i32_e32 v29, 31, v28
	v_lshl_add_u64 v[74:75], v[28:29], 2, s[14:15]
	s_and_saveexec_b64 s[18:19], s[4:5]
	global_store_dword v[74:75], v32, off
	s_or_b64 exec, exec, s[18:19]
	v_add_f32_e32 v24, v32, v98
	v_max_f32_e32 v26, v99, v99
	v_max_f32_e32 v32, v24, v26
	v_sub_f32_e32 v24, v24, v32
	v_sub_f32_e32 v25, v99, v32
	v_mul_f32_e32 v24, 0x3fb8aa3b, v24
	v_mul_f32_e32 v25, 0x3fb8aa3b, v25
	v_exp_f32_e32 v24, v24
	v_exp_f32_e32 v26, v25
	s_nop 0
	v_mov_b32_e32 v25, v24
	v_mov_b32_e32 v27, v26
	s_and_saveexec_b64 s[18:19], vcc
	global_store_dwordx4 v[162:163], v[0:3], off
	global_store_dwordx4 v[162:163], v[4:7], off offset:16
	v_pk_mul_f32 v[158:159], v[26:27], v[158:159]
	v_pk_mul_f32 v[160:161], v[26:27], v[160:161]
	v_pk_mul_f32 v[154:155], v[26:27], v[154:155]
	v_pk_mul_f32 v[156:157], v[26:27], v[156:157]
	s_nop 1
	v_pk_fma_f32 v[0:1], v[0:1], v[24:25], v[158:159]
	v_pk_fma_f32 v[2:3], v[2:3], v[24:25], v[160:161]
	v_pk_fma_f32 v[4:5], v[4:5], v[24:25], v[154:155]
	v_pk_fma_f32 v[6:7], v[6:7], v[24:25], v[156:157]
	s_or_b64 exec, exec, s[18:19]
	v_lshlrev_b32_e32 v28, 16, v100
	v_and_b32_e32 v29, 0xffff0000, v100
	v_lshlrev_b32_e32 v8, 16, v101
	v_and_b32_e32 v9, 0xffff0000, v101
	v_pk_mul_f32 v[8:9], v[26:27], v[8:9]
	v_pk_mul_f32 v[28:29], v[26:27], v[28:29]
	v_pk_fma_f32 v[20:21], v[20:21], v[24:25], v[8:9]
	v_lshlrev_b32_e32 v8, 16, v102
	v_and_b32_e32 v9, 0xffff0000, v102
	v_pk_mul_f32 v[8:9], v[26:27], v[8:9]
	s_nop 0
	v_pk_fma_f32 v[22:23], v[22:23], v[24:25], v[8:9]
	v_lshlrev_b32_e32 v8, 16, v103
	v_and_b32_e32 v9, 0xffff0000, v103
	v_pk_mul_f32 v[8:9], v[26:27], v[8:9]
	v_pk_fma_f32 v[18:19], v[18:19], v[24:25], v[28:29]
	s_nop 0
	v_pk_fma_f32 v[16:17], v[16:17], v[24:25], v[8:9]
	s_add_i32 s23, s21, 4
	s_min_u32 s23, s23, 63
	s_sub_i32 s24, 63, s23
	v_mov_b32_e32 v8, s24
	v_mov_b32_e32 v9, s23
	v_cndmask_b32_e64 v8, v8, v9, s[2:3]
	v_or_b32_e32 v28, v8, v31
	v_mov_b32_e32 v106, v28
	v_lshlrev_b32_e32 v8, 1, v28
	v_ashrrev_i32_e32 v9, 31, v8
	v_lshl_add_u64 v[8:9], v[8:9], 2, s[12:13]
	v_ashrrev_i32_e32 v29, 31, v28
	global_load_dwordx2 v[98:99], v[8:9], off
	v_lshlrev_b64 v[8:9], 15, v[28:29]
	v_lshl_add_u64 v[104:105], v[12:13], 0, v[8:9]
	global_load_dwordx4 v[100:103], v[104:105], off
	v_lshlrev_b64 v[8:9], 9, v[28:29]
	v_lshl_add_u64 v[162:163], v[14:15], 0, v[8:9]
	s_and_saveexec_b64 s[18:19], vcc
	global_load_dwordx4 v[154:157], v[162:163], off offset:16
	global_load_dwordx4 v[158:161], v[162:163], off
	s_or_b64 exec, exec, s[18:19]
	s_waitcnt vmcnt(16)
	v_cvt_pk_bf16_f32 v34, v18, v19
	v_cvt_pk_bf16_f32 v35, v20, v21
	v_cvt_pk_bf16_f32 v36, v22, v23
	v_cvt_pk_bf16_f32 v37, v16, v17
	global_store_dwordx4 v[114:115], v[34:37], off
	v_mov_b32_e32 v28, v116
	v_ashrrev_i32_e32 v29, 31, v28
	v_lshl_add_u64 v[74:75], v[28:29], 2, s[14:15]
	s_and_saveexec_b64 s[18:19], s[4:5]
	global_store_dword v[74:75], v32, off
	s_or_b64 exec, exec, s[18:19]
	v_add_f32_e32 v24, v32, v108
	v_max_f32_e32 v26, v109, v109
	v_max_f32_e32 v32, v24, v26
	v_sub_f32_e32 v24, v24, v32
	v_sub_f32_e32 v25, v109, v32
	v_mul_f32_e32 v24, 0x3fb8aa3b, v24
	v_mul_f32_e32 v25, 0x3fb8aa3b, v25
	v_exp_f32_e32 v24, v24
	v_exp_f32_e32 v26, v25
	s_nop 0
	v_mov_b32_e32 v25, v24
	v_mov_b32_e32 v27, v26
	s_and_saveexec_b64 s[18:19], vcc
	global_store_dwordx4 v[172:173], v[0:3], off
	global_store_dwordx4 v[172:173], v[4:7], off offset:16
	v_pk_mul_f32 v[168:169], v[26:27], v[168:169]
	v_pk_mul_f32 v[170:171], v[26:27], v[170:171]
	v_pk_mul_f32 v[164:165], v[26:27], v[164:165]
	v_pk_mul_f32 v[166:167], v[26:27], v[166:167]
	s_nop 1
	v_pk_fma_f32 v[0:1], v[0:1], v[24:25], v[168:169]
	v_pk_fma_f32 v[2:3], v[2:3], v[24:25], v[170:171]
	v_pk_fma_f32 v[4:5], v[4:5], v[24:25], v[164:165]
	v_pk_fma_f32 v[6:7], v[6:7], v[24:25], v[166:167]
	s_or_b64 exec, exec, s[18:19]
	v_lshlrev_b32_e32 v28, 16, v110
	v_and_b32_e32 v29, 0xffff0000, v110
	v_lshlrev_b32_e32 v8, 16, v111
	v_and_b32_e32 v9, 0xffff0000, v111
	v_pk_mul_f32 v[8:9], v[26:27], v[8:9]
	v_pk_mul_f32 v[28:29], v[26:27], v[28:29]
	v_pk_fma_f32 v[20:21], v[20:21], v[24:25], v[8:9]
	v_lshlrev_b32_e32 v8, 16, v112
	v_and_b32_e32 v9, 0xffff0000, v112
	v_pk_mul_f32 v[8:9], v[26:27], v[8:9]
	s_nop 0
	v_pk_fma_f32 v[22:23], v[22:23], v[24:25], v[8:9]
	v_lshlrev_b32_e32 v8, 16, v113
	v_and_b32_e32 v9, 0xffff0000, v113
	v_pk_mul_f32 v[8:9], v[26:27], v[8:9]
	v_pk_fma_f32 v[18:19], v[18:19], v[24:25], v[28:29]
	s_nop 0
	v_pk_fma_f32 v[16:17], v[16:17], v[24:25], v[8:9]
	s_add_i32 s23, s21, 5
	s_min_u32 s23, s23, 63
	s_sub_i32 s24, 63, s23
	v_mov_b32_e32 v8, s24
	v_mov_b32_e32 v9, s23
	v_cndmask_b32_e64 v8, v8, v9, s[2:3]
	v_or_b32_e32 v28, v8, v31
	v_mov_b32_e32 v116, v28
	v_lshlrev_b32_e32 v8, 1, v28
	v_ashrrev_i32_e32 v9, 31, v8
	v_lshl_add_u64 v[8:9], v[8:9], 2, s[12:13]
	v_ashrrev_i32_e32 v29, 31, v28
	global_load_dwordx2 v[108:109], v[8:9], off
	v_lshlrev_b64 v[8:9], 15, v[28:29]
	v_lshl_add_u64 v[114:115], v[12:13], 0, v[8:9]
	global_load_dwordx4 v[110:113], v[114:115], off
	v_lshlrev_b64 v[8:9], 9, v[28:29]
	v_lshl_add_u64 v[172:173], v[14:15], 0, v[8:9]
	s_and_saveexec_b64 s[18:19], vcc
	global_load_dwordx4 v[164:167], v[172:173], off offset:16
	global_load_dwordx4 v[168:171], v[172:173], off
	s_or_b64 exec, exec, s[18:19]
	s_waitcnt vmcnt(20)
	v_cvt_pk_bf16_f32 v34, v18, v19
	v_cvt_pk_bf16_f32 v35, v20, v21
	v_cvt_pk_bf16_f32 v36, v22, v23
	v_cvt_pk_bf16_f32 v37, v16, v17
	global_store_dwordx4 v[140:141], v[34:37], off
	v_mov_b32_e32 v28, v142
	v_ashrrev_i32_e32 v29, 31, v28
	v_lshl_add_u64 v[74:75], v[28:29], 2, s[14:15]
	s_and_saveexec_b64 s[18:19], s[4:5]
	global_store_dword v[74:75], v32, off
	s_or_b64 exec, exec, s[18:19]
	v_add_f32_e32 v24, v32, v134
	v_max_f32_e32 v26, v135, v135
	v_max_f32_e32 v32, v24, v26
	v_sub_f32_e32 v24, v24, v32
	v_sub_f32_e32 v25, v135, v32
	v_mul_f32_e32 v24, 0x3fb8aa3b, v24
	v_mul_f32_e32 v25, 0x3fb8aa3b, v25
	v_exp_f32_e32 v24, v24
	v_exp_f32_e32 v26, v25
	s_nop 0
	v_mov_b32_e32 v25, v24
	v_mov_b32_e32 v27, v26
	s_and_saveexec_b64 s[18:19], vcc
	global_store_dwordx4 v[186:187], v[0:3], off
	global_store_dwordx4 v[186:187], v[4:7], off offset:16
	v_pk_mul_f32 v[182:183], v[26:27], v[182:183]
	v_pk_mul_f32 v[184:185], v[26:27], v[184:185]
	v_pk_mul_f32 v[178:179], v[26:27], v[178:179]
	v_pk_mul_f32 v[180:181], v[26:27], v[180:181]
	s_nop 1
	v_pk_fma_f32 v[0:1], v[0:1], v[24:25], v[182:183]
	v_pk_fma_f32 v[2:3], v[2:3], v[24:25], v[184:185]
	v_pk_fma_f32 v[4:5], v[4:5], v[24:25], v[178:179]
	v_pk_fma_f32 v[6:7], v[6:7], v[24:25], v[180:181]
	s_or_b64 exec, exec, s[18:19]
	v_lshlrev_b32_e32 v28, 16, v136
	v_and_b32_e32 v29, 0xffff0000, v136
	v_lshlrev_b32_e32 v8, 16, v137
	v_and_b32_e32 v9, 0xffff0000, v137
	v_pk_mul_f32 v[8:9], v[26:27], v[8:9]
	v_pk_mul_f32 v[28:29], v[26:27], v[28:29]
	v_pk_fma_f32 v[20:21], v[20:21], v[24:25], v[8:9]
	v_lshlrev_b32_e32 v8, 16, v138
	v_and_b32_e32 v9, 0xffff0000, v138
	v_pk_mul_f32 v[8:9], v[26:27], v[8:9]
	s_nop 0
	v_pk_fma_f32 v[22:23], v[22:23], v[24:25], v[8:9]
	v_lshlrev_b32_e32 v8, 16, v139
	v_and_b32_e32 v9, 0xffff0000, v139
	v_pk_mul_f32 v[8:9], v[26:27], v[8:9]
	v_pk_fma_f32 v[18:19], v[18:19], v[24:25], v[28:29]
	s_nop 0
	v_pk_fma_f32 v[16:17], v[16:17], v[24:25], v[8:9]
	s_add_i32 s23, s21, 6
	s_min_u32 s23, s23, 63
	s_sub_i32 s24, 63, s23
	v_mov_b32_e32 v8, s24
	v_mov_b32_e32 v9, s23
	v_cndmask_b32_e64 v8, v8, v9, s[2:3]
	v_or_b32_e32 v28, v8, v31
	v_mov_b32_e32 v142, v28
	v_lshlrev_b32_e32 v8, 1, v28
	v_ashrrev_i32_e32 v9, 31, v8
	v_lshl_add_u64 v[8:9], v[8:9], 2, s[12:13]
	v_ashrrev_i32_e32 v29, 31, v28
	global_load_dwordx2 v[134:135], v[8:9], off
	v_lshlrev_b64 v[8:9], 15, v[28:29]
	v_lshl_add_u64 v[140:141], v[12:13], 0, v[8:9]
	global_load_dwordx4 v[136:139], v[140:141], off
	v_lshlrev_b64 v[8:9], 9, v[28:29]
	v_lshl_add_u64 v[186:187], v[14:15], 0, v[8:9]
	s_and_saveexec_b64 s[18:19], vcc
	global_load_dwordx4 v[178:181], v[186:187], off offset:16
	global_load_dwordx4 v[182:185], v[186:187], off
	s_or_b64 exec, exec, s[18:19]
	s_waitcnt vmcnt(24)
	v_cvt_pk_bf16_f32 v34, v18, v19
	v_cvt_pk_bf16_f32 v35, v20, v21
	v_cvt_pk_bf16_f32 v36, v22, v23
	v_cvt_pk_bf16_f32 v37, v16, v17
	global_store_dwordx4 v[150:151], v[34:37], off
	v_mov_b32_e32 v28, v152
	v_ashrrev_i32_e32 v29, 31, v28
	v_lshl_add_u64 v[74:75], v[28:29], 2, s[14:15]
	s_and_saveexec_b64 s[18:19], s[4:5]
	global_store_dword v[74:75], v32, off
	s_or_b64 exec, exec, s[18:19]
	v_add_f32_e32 v24, v32, v144
	v_max_f32_e32 v26, v145, v145
	v_max_f32_e32 v32, v24, v26
	v_sub_f32_e32 v24, v24, v32
	v_sub_f32_e32 v25, v145, v32
	v_mul_f32_e32 v24, 0x3fb8aa3b, v24
	v_mul_f32_e32 v25, 0x3fb8aa3b, v25
	v_exp_f32_e32 v24, v24
	v_exp_f32_e32 v26, v25
	s_nop 0
	v_mov_b32_e32 v25, v24
	v_mov_b32_e32 v27, v26
	s_and_saveexec_b64 s[18:19], vcc
	global_store_dwordx4 v[196:197], v[0:3], off
	global_store_dwordx4 v[196:197], v[4:7], off offset:16
	v_pk_mul_f32 v[192:193], v[26:27], v[192:193]
	v_pk_mul_f32 v[194:195], v[26:27], v[194:195]
	v_pk_mul_f32 v[188:189], v[26:27], v[188:189]
	v_pk_mul_f32 v[190:191], v[26:27], v[190:191]
	s_nop 1
	v_pk_fma_f32 v[0:1], v[0:1], v[24:25], v[192:193]
	v_pk_fma_f32 v[2:3], v[2:3], v[24:25], v[194:195]
	v_pk_fma_f32 v[4:5], v[4:5], v[24:25], v[188:189]
	v_pk_fma_f32 v[6:7], v[6:7], v[24:25], v[190:191]
	s_or_b64 exec, exec, s[18:19]
	v_lshlrev_b32_e32 v28, 16, v146
	v_and_b32_e32 v29, 0xffff0000, v146
	v_lshlrev_b32_e32 v8, 16, v147
	v_and_b32_e32 v9, 0xffff0000, v147
	v_pk_mul_f32 v[8:9], v[26:27], v[8:9]
	v_pk_mul_f32 v[28:29], v[26:27], v[28:29]
	v_pk_fma_f32 v[20:21], v[20:21], v[24:25], v[8:9]
	v_lshlrev_b32_e32 v8, 16, v148
	v_and_b32_e32 v9, 0xffff0000, v148
	v_pk_mul_f32 v[8:9], v[26:27], v[8:9]
	s_nop 0
	v_pk_fma_f32 v[22:23], v[22:23], v[24:25], v[8:9]
	v_lshlrev_b32_e32 v8, 16, v149
	v_and_b32_e32 v9, 0xffff0000, v149
	v_pk_mul_f32 v[8:9], v[26:27], v[8:9]
	v_pk_fma_f32 v[18:19], v[18:19], v[24:25], v[28:29]
	s_nop 0
	v_pk_fma_f32 v[16:17], v[16:17], v[24:25], v[8:9]
	s_add_i32 s23, s21, 7
	s_min_u32 s23, s23, 63
	s_sub_i32 s24, 63, s23
	v_mov_b32_e32 v8, s24
	v_mov_b32_e32 v9, s23
	v_cndmask_b32_e64 v8, v8, v9, s[2:3]
	v_or_b32_e32 v28, v8, v31
	v_mov_b32_e32 v152, v28
	v_lshlrev_b32_e32 v8, 1, v28
	v_ashrrev_i32_e32 v9, 31, v8
	v_lshl_add_u64 v[8:9], v[8:9], 2, s[12:13]
	v_ashrrev_i32_e32 v29, 31, v28
	global_load_dwordx2 v[144:145], v[8:9], off
	v_lshlrev_b64 v[8:9], 15, v[28:29]
	v_lshl_add_u64 v[150:151], v[12:13], 0, v[8:9]
	global_load_dwordx4 v[146:149], v[150:151], off
	v_lshlrev_b64 v[8:9], 9, v[28:29]
	v_lshl_add_u64 v[196:197], v[14:15], 0, v[8:9]
	s_and_saveexec_b64 s[18:19], vcc
	global_load_dwordx4 v[188:191], v[196:197], off offset:16
	global_load_dwordx4 v[192:195], v[196:197], off
	s_or_b64 exec, exec, s[18:19]
	s_mov_b32 s21, 4
.Lscan_B_loop:
	s_waitcnt vmcnt(24)
	v_cvt_pk_bf16_f32 v34, v18, v19
	v_cvt_pk_bf16_f32 v35, v20, v21
	v_cvt_pk_bf16_f32 v36, v22, v23
	v_cvt_pk_bf16_f32 v37, v16, v17
	global_store_dwordx4 v[104:105], v[34:37], off
	v_mov_b32_e32 v28, v106
	v_ashrrev_i32_e32 v29, 31, v28
	v_lshl_add_u64 v[74:75], v[28:29], 2, s[14:15]
	s_and_saveexec_b64 s[18:19], s[4:5]
	global_store_dword v[74:75], v32, off
	s_or_b64 exec, exec, s[18:19]
	v_add_f32_e32 v24, v32, v98
	v_max_f32_e32 v26, v99, v99
	v_max_f32_e32 v32, v24, v26
	v_sub_f32_e32 v24, v24, v32
	v_sub_f32_e32 v25, v99, v32
	v_mul_f32_e32 v24, 0x3fb8aa3b, v24
	v_mul_f32_e32 v25, 0x3fb8aa3b, v25
	v_exp_f32_e32 v24, v24
	v_exp_f32_e32 v26, v25
	s_nop 0
	v_mov_b32_e32 v25, v24
	v_mov_b32_e32 v27, v26
	s_and_saveexec_b64 s[18:19], vcc
	global_store_dwordx4 v[162:163], v[0:3], off
	global_store_dwordx4 v[162:163], v[4:7], off offset:16
	v_pk_mul_f32 v[158:159], v[26:27], v[158:159]
	v_pk_mul_f32 v[160:161], v[26:27], v[160:161]
	v_pk_mul_f32 v[154:155], v[26:27], v[154:155]
	v_pk_mul_f32 v[156:157], v[26:27], v[156:157]
	s_nop 1
	v_pk_fma_f32 v[0:1], v[0:1], v[24:25], v[158:159]
	v_pk_fma_f32 v[2:3], v[2:3], v[24:25], v[160:161]
	v_pk_fma_f32 v[4:5], v[4:5], v[24:25], v[154:155]
	v_pk_fma_f32 v[6:7], v[6:7], v[24:25], v[156:157]
	s_or_b64 exec, exec, s[18:19]
	v_lshlrev_b32_e32 v28, 16, v100
	v_and_b32_e32 v29, 0xffff0000, v100
	v_lshlrev_b32_e32 v8, 16, v101
	v_and_b32_e32 v9, 0xffff0000, v101
	v_pk_mul_f32 v[8:9], v[26:27], v[8:9]
	v_pk_mul_f32 v[28:29], v[26:27], v[28:29]
	v_pk_fma_f32 v[20:21], v[20:21], v[24:25], v[8:9]
	v_lshlrev_b32_e32 v8, 16, v102
	v_and_b32_e32 v9, 0xffff0000, v102
	v_pk_mul_f32 v[8:9], v[26:27], v[8:9]
	s_nop 0
	v_pk_fma_f32 v[22:23], v[22:23], v[24:25], v[8:9]
	v_lshlrev_b32_e32 v8, 16, v103
	v_and_b32_e32 v9, 0xffff0000, v103
	v_pk_mul_f32 v[8:9], v[26:27], v[8:9]
	v_pk_fma_f32 v[18:19], v[18:19], v[24:25], v[28:29]
	s_nop 0
	v_pk_fma_f32 v[16:17], v[16:17], v[24:25], v[8:9]
	s_add_i32 s23, s21, 4
	s_min_u32 s23, s23, 63
	s_sub_i32 s24, 63, s23
	v_mov_b32_e32 v8, s24
	v_mov_b32_e32 v9, s23
	v_cndmask_b32_e64 v8, v8, v9, s[2:3]
	v_or_b32_e32 v28, v8, v31
	v_mov_b32_e32 v106, v28
	v_lshlrev_b32_e32 v8, 1, v28
	v_ashrrev_i32_e32 v9, 31, v8
	v_lshl_add_u64 v[8:9], v[8:9], 2, s[12:13]
	v_ashrrev_i32_e32 v29, 31, v28
	global_load_dwordx2 v[98:99], v[8:9], off
	v_lshlrev_b64 v[8:9], 15, v[28:29]
	v_lshl_add_u64 v[104:105], v[12:13], 0, v[8:9]
	global_load_dwordx4 v[100:103], v[104:105], off
	v_lshlrev_b64 v[8:9], 9, v[28:29]
	v_lshl_add_u64 v[162:163], v[14:15], 0, v[8:9]
	s_and_saveexec_b64 s[18:19], vcc
	global_load_dwordx4 v[154:157], v[162:163], off offset:16
	global_load_dwordx4 v[158:161], v[162:163], off
	s_or_b64 exec, exec, s[18:19]
	s_waitcnt vmcnt(24)
	v_cvt_pk_bf16_f32 v34, v18, v19
	v_cvt_pk_bf16_f32 v35, v20, v21
	v_cvt_pk_bf16_f32 v36, v22, v23
	v_cvt_pk_bf16_f32 v37, v16, v17
	global_store_dwordx4 v[114:115], v[34:37], off
	v_mov_b32_e32 v28, v116
	v_ashrrev_i32_e32 v29, 31, v28
	v_lshl_add_u64 v[74:75], v[28:29], 2, s[14:15]
	s_and_saveexec_b64 s[18:19], s[4:5]
	global_store_dword v[74:75], v32, off
	s_or_b64 exec, exec, s[18:19]
	v_add_f32_e32 v24, v32, v108
	v_max_f32_e32 v26, v109, v109
	v_max_f32_e32 v32, v24, v26
	v_sub_f32_e32 v24, v24, v32
	v_sub_f32_e32 v25, v109, v32
	v_mul_f32_e32 v24, 0x3fb8aa3b, v24
	v_mul_f32_e32 v25, 0x3fb8aa3b, v25
	v_exp_f32_e32 v24, v24
	v_exp_f32_e32 v26, v25
	s_nop 0
	v_mov_b32_e32 v25, v24
	v_mov_b32_e32 v27, v26
	s_and_saveexec_b64 s[18:19], vcc
	global_store_dwordx4 v[172:173], v[0:3], off
	global_store_dwordx4 v[172:173], v[4:7], off offset:16
	v_pk_mul_f32 v[168:169], v[26:27], v[168:169]
	v_pk_mul_f32 v[170:171], v[26:27], v[170:171]
	v_pk_mul_f32 v[164:165], v[26:27], v[164:165]
	v_pk_mul_f32 v[166:167], v[26:27], v[166:167]
	s_nop 1
	v_pk_fma_f32 v[0:1], v[0:1], v[24:25], v[168:169]
	v_pk_fma_f32 v[2:3], v[2:3], v[24:25], v[170:171]
	v_pk_fma_f32 v[4:5], v[4:5], v[24:25], v[164:165]
	v_pk_fma_f32 v[6:7], v[6:7], v[24:25], v[166:167]
	s_or_b64 exec, exec, s[18:19]
	v_lshlrev_b32_e32 v28, 16, v110
	v_and_b32_e32 v29, 0xffff0000, v110
	v_lshlrev_b32_e32 v8, 16, v111
	v_and_b32_e32 v9, 0xffff0000, v111
	v_pk_mul_f32 v[8:9], v[26:27], v[8:9]
	v_pk_mul_f32 v[28:29], v[26:27], v[28:29]
	v_pk_fma_f32 v[20:21], v[20:21], v[24:25], v[8:9]
	v_lshlrev_b32_e32 v8, 16, v112
	v_and_b32_e32 v9, 0xffff0000, v112
	v_pk_mul_f32 v[8:9], v[26:27], v[8:9]
	s_nop 0
	v_pk_fma_f32 v[22:23], v[22:23], v[24:25], v[8:9]
	v_lshlrev_b32_e32 v8, 16, v113
	v_and_b32_e32 v9, 0xffff0000, v113
	v_pk_mul_f32 v[8:9], v[26:27], v[8:9]
	v_pk_fma_f32 v[18:19], v[18:19], v[24:25], v[28:29]
	s_nop 0
	v_pk_fma_f32 v[16:17], v[16:17], v[24:25], v[8:9]
	s_add_i32 s23, s21, 5
	s_min_u32 s23, s23, 63
	s_sub_i32 s24, 63, s23
	v_mov_b32_e32 v8, s24
	v_mov_b32_e32 v9, s23
	v_cndmask_b32_e64 v8, v8, v9, s[2:3]
	v_or_b32_e32 v28, v8, v31
	v_mov_b32_e32 v116, v28
	v_lshlrev_b32_e32 v8, 1, v28
	v_ashrrev_i32_e32 v9, 31, v8
	v_lshl_add_u64 v[8:9], v[8:9], 2, s[12:13]
	v_ashrrev_i32_e32 v29, 31, v28
	global_load_dwordx2 v[108:109], v[8:9], off
	v_lshlrev_b64 v[8:9], 15, v[28:29]
	v_lshl_add_u64 v[114:115], v[12:13], 0, v[8:9]
	global_load_dwordx4 v[110:113], v[114:115], off
	v_lshlrev_b64 v[8:9], 9, v[28:29]
	v_lshl_add_u64 v[172:173], v[14:15], 0, v[8:9]
	s_and_saveexec_b64 s[18:19], vcc
	global_load_dwordx4 v[164:167], v[172:173], off offset:16
	global_load_dwordx4 v[168:171], v[172:173], off
	s_or_b64 exec, exec, s[18:19]
	s_waitcnt vmcnt(24)
	v_cvt_pk_bf16_f32 v34, v18, v19
	v_cvt_pk_bf16_f32 v35, v20, v21
	v_cvt_pk_bf16_f32 v36, v22, v23
	v_cvt_pk_bf16_f32 v37, v16, v17
	global_store_dwordx4 v[140:141], v[34:37], off
	v_mov_b32_e32 v28, v142
	v_ashrrev_i32_e32 v29, 31, v28
	v_lshl_add_u64 v[74:75], v[28:29], 2, s[14:15]
	s_and_saveexec_b64 s[18:19], s[4:5]
	global_store_dword v[74:75], v32, off
	s_or_b64 exec, exec, s[18:19]
	v_add_f32_e32 v24, v32, v134
	v_max_f32_e32 v26, v135, v135
	v_max_f32_e32 v32, v24, v26
	v_sub_f32_e32 v24, v24, v32
	v_sub_f32_e32 v25, v135, v32
	v_mul_f32_e32 v24, 0x3fb8aa3b, v24
	v_mul_f32_e32 v25, 0x3fb8aa3b, v25
	v_exp_f32_e32 v24, v24
	v_exp_f32_e32 v26, v25
	s_nop 0
	v_mov_b32_e32 v25, v24
	v_mov_b32_e32 v27, v26
	s_and_saveexec_b64 s[18:19], vcc
	global_store_dwordx4 v[186:187], v[0:3], off
	global_store_dwordx4 v[186:187], v[4:7], off offset:16
	v_pk_mul_f32 v[182:183], v[26:27], v[182:183]
	v_pk_mul_f32 v[184:185], v[26:27], v[184:185]
	v_pk_mul_f32 v[178:179], v[26:27], v[178:179]
	v_pk_mul_f32 v[180:181], v[26:27], v[180:181]
	s_nop 1
	v_pk_fma_f32 v[0:1], v[0:1], v[24:25], v[182:183]
	v_pk_fma_f32 v[2:3], v[2:3], v[24:25], v[184:185]
	v_pk_fma_f32 v[4:5], v[4:5], v[24:25], v[178:179]
	v_pk_fma_f32 v[6:7], v[6:7], v[24:25], v[180:181]
	s_or_b64 exec, exec, s[18:19]
	v_lshlrev_b32_e32 v28, 16, v136
	v_and_b32_e32 v29, 0xffff0000, v136
	v_lshlrev_b32_e32 v8, 16, v137
	v_and_b32_e32 v9, 0xffff0000, v137
	v_pk_mul_f32 v[8:9], v[26:27], v[8:9]
	v_pk_mul_f32 v[28:29], v[26:27], v[28:29]
	v_pk_fma_f32 v[20:21], v[20:21], v[24:25], v[8:9]
	v_lshlrev_b32_e32 v8, 16, v138
	v_and_b32_e32 v9, 0xffff0000, v138
	v_pk_mul_f32 v[8:9], v[26:27], v[8:9]
	s_nop 0
	v_pk_fma_f32 v[22:23], v[22:23], v[24:25], v[8:9]
	v_lshlrev_b32_e32 v8, 16, v139
	v_and_b32_e32 v9, 0xffff0000, v139
	v_pk_mul_f32 v[8:9], v[26:27], v[8:9]
	v_pk_fma_f32 v[18:19], v[18:19], v[24:25], v[28:29]
	s_nop 0
	v_pk_fma_f32 v[16:17], v[16:17], v[24:25], v[8:9]
	s_add_i32 s23, s21, 6
	s_min_u32 s23, s23, 63
	s_sub_i32 s24, 63, s23
	v_mov_b32_e32 v8, s24
	v_mov_b32_e32 v9, s23
	v_cndmask_b32_e64 v8, v8, v9, s[2:3]
	v_or_b32_e32 v28, v8, v31
	v_mov_b32_e32 v142, v28
	v_lshlrev_b32_e32 v8, 1, v28
	v_ashrrev_i32_e32 v9, 31, v8
	v_lshl_add_u64 v[8:9], v[8:9], 2, s[12:13]
	v_ashrrev_i32_e32 v29, 31, v28
	global_load_dwordx2 v[134:135], v[8:9], off
	v_lshlrev_b64 v[8:9], 15, v[28:29]
	v_lshl_add_u64 v[140:141], v[12:13], 0, v[8:9]
	global_load_dwordx4 v[136:139], v[140:141], off
	v_lshlrev_b64 v[8:9], 9, v[28:29]
	v_lshl_add_u64 v[186:187], v[14:15], 0, v[8:9]
	s_and_saveexec_b64 s[18:19], vcc
	global_load_dwordx4 v[178:181], v[186:187], off offset:16
	global_load_dwordx4 v[182:185], v[186:187], off
	s_or_b64 exec, exec, s[18:19]
	s_waitcnt vmcnt(24)
	v_cvt_pk_bf16_f32 v34, v18, v19
	v_cvt_pk_bf16_f32 v35, v20, v21
	v_cvt_pk_bf16_f32 v36, v22, v23
	v_cvt_pk_bf16_f32 v37, v16, v17
	global_store_dwordx4 v[150:151], v[34:37], off
	v_mov_b32_e32 v28, v152
	v_ashrrev_i32_e32 v29, 31, v28
	v_lshl_add_u64 v[74:75], v[28:29], 2, s[14:15]
	s_and_saveexec_b64 s[18:19], s[4:5]
	global_store_dword v[74:75], v32, off
	s_or_b64 exec, exec, s[18:19]
	v_add_f32_e32 v24, v32, v144
	v_max_f32_e32 v26, v145, v145
	v_max_f32_e32 v32, v24, v26
	v_sub_f32_e32 v24, v24, v32
	v_sub_f32_e32 v25, v145, v32
	v_mul_f32_e32 v24, 0x3fb8aa3b, v24
	v_mul_f32_e32 v25, 0x3fb8aa3b, v25
	v_exp_f32_e32 v24, v24
	v_exp_f32_e32 v26, v25
	s_nop 0
	v_mov_b32_e32 v25, v24
	v_mov_b32_e32 v27, v26
	s_and_saveexec_b64 s[18:19], vcc
	global_store_dwordx4 v[196:197], v[0:3], off
	global_store_dwordx4 v[196:197], v[4:7], off offset:16
	v_pk_mul_f32 v[192:193], v[26:27], v[192:193]
	v_pk_mul_f32 v[194:195], v[26:27], v[194:195]
	v_pk_mul_f32 v[188:189], v[26:27], v[188:189]
	v_pk_mul_f32 v[190:191], v[26:27], v[190:191]
	s_nop 1
	v_pk_fma_f32 v[0:1], v[0:1], v[24:25], v[192:193]
	v_pk_fma_f32 v[2:3], v[2:3], v[24:25], v[194:195]
	v_pk_fma_f32 v[4:5], v[4:5], v[24:25], v[188:189]
	v_pk_fma_f32 v[6:7], v[6:7], v[24:25], v[190:191]
	s_or_b64 exec, exec, s[18:19]
	v_lshlrev_b32_e32 v28, 16, v146
	v_and_b32_e32 v29, 0xffff0000, v146
	v_lshlrev_b32_e32 v8, 16, v147
	v_and_b32_e32 v9, 0xffff0000, v147
	v_pk_mul_f32 v[8:9], v[26:27], v[8:9]
	v_pk_mul_f32 v[28:29], v[26:27], v[28:29]
	v_pk_fma_f32 v[20:21], v[20:21], v[24:25], v[8:9]
	v_lshlrev_b32_e32 v8, 16, v148
	v_and_b32_e32 v9, 0xffff0000, v148
	v_pk_mul_f32 v[8:9], v[26:27], v[8:9]
	s_nop 0
	v_pk_fma_f32 v[22:23], v[22:23], v[24:25], v[8:9]
	v_lshlrev_b32_e32 v8, 16, v149
	v_and_b32_e32 v9, 0xffff0000, v149
	v_pk_mul_f32 v[8:9], v[26:27], v[8:9]
	v_pk_fma_f32 v[18:19], v[18:19], v[24:25], v[28:29]
	s_nop 0
	v_pk_fma_f32 v[16:17], v[16:17], v[24:25], v[8:9]
	s_add_i32 s23, s21, 7
	s_min_u32 s23, s23, 63
	s_sub_i32 s24, 63, s23
	v_mov_b32_e32 v8, s24
	v_mov_b32_e32 v9, s23
	v_cndmask_b32_e64 v8, v8, v9, s[2:3]
	v_or_b32_e32 v28, v8, v31
	v_mov_b32_e32 v152, v28
	v_lshlrev_b32_e32 v8, 1, v28
	v_ashrrev_i32_e32 v9, 31, v8
	v_lshl_add_u64 v[8:9], v[8:9], 2, s[12:13]
	v_ashrrev_i32_e32 v29, 31, v28
	global_load_dwordx2 v[144:145], v[8:9], off
	v_lshlrev_b64 v[8:9], 15, v[28:29]
	v_lshl_add_u64 v[150:151], v[12:13], 0, v[8:9]
	global_load_dwordx4 v[146:149], v[150:151], off
	v_lshlrev_b64 v[8:9], 9, v[28:29]
	v_lshl_add_u64 v[196:197], v[14:15], 0, v[8:9]
	s_and_saveexec_b64 s[18:19], vcc
	global_load_dwordx4 v[188:191], v[196:197], off offset:16
	global_load_dwordx4 v[192:195], v[196:197], off
	s_or_b64 exec, exec, s[18:19]
	s_add_i32 s21, s21, 4
	s_cmp_lt_u32 s21, 64
	s_cbranch_scc1 .Lscan_B_loop
	s_branch .LBB0_1130

.LBB0_1248:
	v_add_co_u32_e32 v210, vcc, 0xfffa0000, v210
	s_nop 1
	v_addc_co_u32_e32 v211, vcc, -1, v211, vcc
	v_add_co_u32_e32 v208, vcc, 0xffffff80, v208
	s_nop 1
	v_addc_co_u32_e32 v209, vcc, -1, v209, vcc
	v_mbcnt_lo_u32_b32 v249, -1, 0
	v_mbcnt_hi_u32_b32 v249, -1, v249
	v_and_b32_e32 v250, 15, v249
	v_bfe_u32 v249, v249, 4, 1
	v_cmp_eq_u32_e32 vcc, v249, v250
	v_mov_b32_e32 v249, s68
	s_nop 1
	v_cndmask_b32_e32 v244, 0, v249, vcc
	v_cndmask_b32_e32 v245, 0, v249, vcc
	v_cndmask_b32_e32 v246, 0, v249, vcc
	v_cndmask_b32_e32 v247, 0, v249, vcc
	v_add_u32_e32 v248, s21, v217
	ds_read_b128 v[226:229], v248 offset:17408
	ds_read_b128 v[230:233], v248 offset:22016
	ds_read_b128 v[236:239], v248 offset:17440
	ds_read_b128 v[240:243], v248 offset:22048
	s_add_i32 s4, s21, 0x8c00
	s_cmp_lg_u32 s21, 0x11800
	s_cselect_b32 s4, s4, 0
	v_exp_f32_e32 v64, v64
	v_exp_f32_e32 v65, v65
	v_exp_f32_e32 v66, v66
	v_exp_f32_e32 v67, v67
	v_exp_f32_e32 v68, v68
	v_exp_f32_e32 v69, v69
	v_exp_f32_e32 v70, v70
	v_exp_f32_e32 v71, v71
	v_cvt_pk_bf16_f32 v64, v64, v65
	v_cvt_pk_bf16_f32 v65, v66, v67
	v_cvt_pk_bf16_f32 v66, v68, v69
	v_cvt_pk_bf16_f32 v67, v70, v71
	s_nop 1
.Lgqa_main:
	v_mfma_f32_16x16x32_bf16 v[96:99], v[244:247], v[64:67], v[96:99]
	v_exp_f32_e32 v72, v72
	v_exp_f32_e32 v73, v73
	v_exp_f32_e32 v74, v74
	s_waitcnt lgkmcnt(3)
	v_mfma_f32_32x32x16_bf16 v[0:15], v[226:229], v[64:67], v[0:15]
	ds_read_b128 v[226:229], v248 offset:17472
	v_add3_u32 v249, s4, v193, v212
	v_add3_u32 v250, s4, v213, v214
	s_waitcnt vmcnt(1)
	ds_write_b128 v249, v[152:155]
	v_exp_f32_e32 v75, v75
	v_exp_f32_e32 v76, v76
	v_exp_f32_e32 v77, v77
	v_cvt_pk_bf16_f32 v72, v72, v73
	s_waitcnt lgkmcnt(4)
	v_mfma_f32_32x32x16_bf16 v[16:31], v[230:233], v[64:67], v[16:31]
	ds_read_b128 v[230:233], v248 offset:22080
	s_waitcnt vmcnt(0)
	ds_write_b128 v250, v[160:163] offset:17408
	v_exp_f32_e32 v78, v78
	v_exp_f32_e32 v79, v79
	v_cvt_pk_bf16_f32 v73, v74, v75
	v_cvt_pk_bf16_f32 v74, v76, v77
	v_cvt_pk_bf16_f32 v75, v78, v79
	s_nop 1
	v_mfma_f32_16x16x32_bf16 v[96:99], v[244:247], v[72:75], v[96:99]
	v_exp_f32_e32 v80, v80
	v_exp_f32_e32 v81, v81
	v_exp_f32_e32 v82, v82
	s_waitcnt lgkmcnt(5)
	v_mfma_f32_32x32x16_bf16 v[0:15], v[236:239], v[72:75], v[0:15]
	ds_read_b128 v[236:239], v248 offset:17504
	v_exp_f32_e32 v83, v83
	v_exp_f32_e32 v84, v84
	v_exp_f32_e32 v85, v85
	v_cvt_pk_bf16_f32 v80, v80, v81
	s_waitcnt lgkmcnt(5)
	v_mfma_f32_32x32x16_bf16 v[16:31], v[240:243], v[72:75], v[16:31]
	ds_read_b128 v[240:243], v248 offset:22112
	v_exp_f32_e32 v86, v86
	v_exp_f32_e32 v87, v87
	v_cvt_pk_bf16_f32 v81, v82, v83
	v_cvt_pk_bf16_f32 v82, v84, v85
	v_cvt_pk_bf16_f32 v83, v86, v87
	s_nop 1
	s_waitcnt lgkmcnt(2)
	s_barrier
	s_cmpk_eq_i32 s23, 0x7f
	s_cbranch_scc1 .Lgqa_last
	s_mov_b64 s[14:15], 0x60000
	s_mov_b64 s[16:17], 0x80
	v_mfma_f32_16x16x32_bf16 v[96:99], v[244:247], v[80:83], v[96:99]
	v_exp_f32_e32 v88, v88
	v_exp_f32_e32 v89, v89
	v_exp_f32_e32 v90, v90
	v_mfma_f32_32x32x16_bf16 v[0:15], v[226:229], v[80:83], v[0:15]
	v_add_u32_e32 v248, s4, v217
	ds_read_b128 v[226:229], v248
	v_exp_f32_e32 v91, v91
	v_exp_f32_e32 v92, v92
	v_exp_f32_e32 v93, v93
	v_cvt_pk_bf16_f32 v88, v88, v89
	v_mfma_f32_32x32x16_bf16 v[16:31], v[230:233], v[80:83], v[16:31]
	ds_read_b128 v[230:233], v248 offset:32
	s_cmpk_gt_u32 s23, 0x7d
	s_cbranch_scc1 .Lgqa_noloada
	global_load_dwordx4 v[152:155], v[210:211], off
	global_load_dwordx4 v[160:163], v[208:209], off
.Lgqa_noloada:
	v_exp_f32_e32 v94, v94
	v_exp_f32_e32 v95, v95
	v_cvt_pk_bf16_f32 v89, v90, v91
	v_cvt_pk_bf16_f32 v90, v92, v93
	v_cvt_pk_bf16_f32 v91, v94, v95
	s_nop 1
	v_mfma_f32_16x16x32_bf16 v[96:99], v[244:247], v[88:91], v[96:99]
	s_add_i32 s23, s23, 1
	v_lshl_add_u64 v[210:211], v[210:211], 0, s[14:15]
	s_waitcnt lgkmcnt(3)
	v_mfma_f32_32x32x16_bf16 v[0:15], v[236:239], v[88:91], v[0:15]
	ds_read_b128 v[236:239], v248 offset:64
	v_lshl_add_u64 v[208:209], v[208:209], 0, s[16:17]
	s_waitcnt lgkmcnt(3)
	v_mfma_f32_32x32x16_bf16 v[16:31], v[240:243], v[88:91], v[16:31]
	ds_read_b128 v[240:243], v248 offset:96
	s_mov_b32 s21, s4
	s_add_i32 s4, s21, 0x8c00
	s_cmp_lg_u32 s21, 0x11800
	s_cselect_b32 s4, s4, 0
	s_waitcnt lgkmcnt(3)
	v_mfma_f32_32x32x16_bf16 v[64:79], v[226:229], v[144:147], v[48:63]
	ds_read_b128 v[226:229], v248 offset:4608
	s_waitcnt lgkmcnt(3)
	v_mfma_f32_32x32x16_bf16 v[64:79], v[230:233], v[148:151], v[64:79]
	ds_read_b128 v[230:233], v248 offset:4640
	s_waitcnt lgkmcnt(3)
	v_mfma_f32_32x32x16_bf16 v[64:79], v[236:239], v[156:159], v[64:79]
	ds_read_b128 v[236:239], v248 offset:4672
	s_waitcnt lgkmcnt(3)
	v_mfma_f32_32x32x16_bf16 v[64:79], v[240:243], v[164:167], v[64:79]
	ds_read_b128 v[240:243], v248 offset:4704
	s_waitcnt lgkmcnt(3)
	v_mfma_f32_32x32x16_bf16 v[80:95], v[226:229], v[144:147], v[48:63]
	ds_read_b128 v[226:229], v248 offset:17408
	s_waitcnt lgkmcnt(3)
	v_mfma_f32_32x32x16_bf16 v[80:95], v[230:233], v[148:151], v[80:95]
	ds_read_b128 v[230:233], v248 offset:22016
	s_nop 4
	v_exp_f32_e32 v64, v64
	v_exp_f32_e32 v65, v65
	v_exp_f32_e32 v66, v66
	s_waitcnt lgkmcnt(3)
	v_mfma_f32_32x32x16_bf16 v[80:95], v[236:239], v[156:159], v[80:95]
	ds_read_b128 v[236:239], v248 offset:17440
	v_exp_f32_e32 v67, v67
	v_exp_f32_e32 v68, v68
	v_exp_f32_e32 v69, v69
	s_waitcnt lgkmcnt(3)
	v_mfma_f32_32x32x16_bf16 v[80:95], v[240:243], v[164:167], v[80:95]
	ds_read_b128 v[240:243], v248 offset:22048
	v_exp_f32_e32 v70, v70
	v_exp_f32_e32 v71, v71
	v_cvt_pk_bf16_f32 v64, v64, v65
	v_cvt_pk_bf16_f32 v65, v66, v67
	v_cvt_pk_bf16_f32 v66, v68, v69
	v_cvt_pk_bf16_f32 v67, v70, v71
	s_nop 1
	s_branch .Lgqa_main
.Lgqa_last:
	v_mfma_f32_16x16x32_bf16 v[96:99], v[244:247], v[80:83], v[96:99]
	v_exp_f32_e32 v88, v88
	v_exp_f32_e32 v89, v89
	v_exp_f32_e32 v90, v90
	v_mfma_f32_32x32x16_bf16 v[0:15], v[226:229], v[80:83], v[0:15]
	v_exp_f32_e32 v91, v91
	v_exp_f32_e32 v92, v92
	v_exp_f32_e32 v93, v93
	v_cvt_pk_bf16_f32 v88, v88, v89
	v_mfma_f32_32x32x16_bf16 v[16:31], v[230:233], v[80:83], v[16:31]
	v_exp_f32_e32 v94, v94
	v_exp_f32_e32 v95, v95
	v_cvt_pk_bf16_f32 v89, v90, v91
	v_cvt_pk_bf16_f32 v90, v92, v93
	v_cvt_pk_bf16_f32 v91, v94, v95
	s_nop 1
	v_mfma_f32_16x16x32_bf16 v[96:99], v[244:247], v[88:91], v[96:99]
	s_waitcnt lgkmcnt(1)
	v_mfma_f32_32x32x16_bf16 v[0:15], v[236:239], v[88:91], v[0:15]
	s_waitcnt lgkmcnt(0)
	v_mfma_f32_32x32x16_bf16 v[16:31], v[240:243], v[88:91], v[16:31]
	v_mbcnt_lo_u32_b32 v249, -1, 0
	v_mbcnt_hi_u32_b32 v249, -1, v249
	v_and_b32_e32 v250, 15, v249
	v_lshlrev_b32_e32 v250, 2, v250
	v_and_b32_e32 v249, 16, v249
	s_nop 3
	v_cmp_ne_u32_e32 vcc, 0, v249
	ds_bpermute_b32 v248, v250, v96
	ds_bpermute_b32 v250, v250, v97
	s_waitcnt lgkmcnt(0)
	v_cndmask_b32_e32 v96, v248, v250, vcc
	s_branch .LBB0_1232
